# v28 + residual epilogues kind 4 (closing-norm gain, second row sum) and kind 5 (lazy closing norm) hand-written the same way, six-row landing ring per half
# speedup vs baseline: 1.0308x; 1.0084x over previous
; #define RES_LD(buf, pp) do { _Pragma("unroll") for (int j = 0; j < 2; ++j) { const int i_ = 2 * (pp) + j; const unsigned off_ = (row0 + (i_ >> 2) * HALF + (i_ & 3) * 16) * 1024u + col; \
;                 xq[buf][j][0] = *(const f32x4*)(xin + off_); xq[buf][j][1] = *(const f32x4*)(xin + off_ + 4); } } while (0)
;     __device__ __forceinline__ unsigned u(int i) const { return (unsigned)__builtin_amdgcn_readfirstlane((int)d[i]); }
;     __device__ __forceinline__ unsigned u(int i) const { return (unsigned)__builtin_amdgcn_readfirstlane((int)d[i]); }
;     static __device__ __forceinline__ void run(const f32x4 (&acc)[2][2][4][2], const Unit& u, int wr, int wc, int fr, int fq, const float* xin, float* xout, const float* gate, float gs, const float* lazy_ssq, const float* lazy_g, ...
;         const unsigned b = (unsigned)(u.pm * BM) >> 13; const unsigned row0 = u.pm * BM + wr * 64 + fr; const unsigned col0 = u.pn * BM + wc * 32 + 8 * fq;
;         float rl[2][4], sq[2][4], sqb[2][4];
; #pragma unroll
;         for (int ai = 0; ai < 2; ++ai)
; #pragma unroll
;             for (int m = 0; m < 4; ++m) { rl[ai][m] = LAZY ? __builtin_amdgcn_rsqf(lazy_ssq[row0 + ai * HALF + m * 16] * (1.0f / 1024.0f) + 1e-6f) : 1.0f; sq[ai][m] = 0.f; sqb[ai][m] = 0.f; }
; #pragma unroll
;         for (int bj = 0; bj < 2; ++bj) {
;             const unsigned col = col0 + bj * HALF;
;             f32x4 gv[2], lg[2], wv[2], w2[2];
; #pragma unroll
;             for (int n = 0; n < 2; ++n) {
;                 gv[n] = *(const f32x4*)(gate + (b * 9216u + col + 4 * n)) * gs;
;                 lg[n] = (f32x4){1.f, 1.f, 1.f, 1.f}; if (LAZY) lg[n] = *(const f32x4*)(lazy_g + col + 4 * n);
;                 wv[n] = (f32x4){0.f, 0.f, 0.f, 0.f}; w2[n] = (f32x4){1.f, 1.f, 1.f, 1.f};
;                 if (aout) { wv[n] = *(const f32x4*)(wg + col + 4 * n) * (*(const f32x4*)(wsc + (b * 9216u + col + 4 * n)) + 1.0f); if (WG2) { w2[n] = *(const f32x4*)(wg2 + col + 4 * n); wv[n] = wv[n] * w2[n]; } }
;             }
;             f32x4 xq[2][2][2];
;     ...
;             constexpr bool DEEP = !LAZY && !WG2;
;             if (DEEP) RES_LD(0, 0);
; #pragma unroll
;             for (int pp = 0; pp < 4; ++pp) {
;                 if (DEEP) { if (pp < 3) RES_LD((pp + 1) & 1, pp + 1); } else RES_LD(pp & 1, pp);
.LBB0_310:
	v_mov_b32_e32 v128, s85
	ds_read_b32 v129, v128
	v_mov_b32_e32 v128, v216
	s_mov_b64 s[8:9], -1
	v_readfirstlane_b32 s2, v128
	s_waitcnt lgkmcnt(0)
	v_readfirstlane_b32 s66, v129
	s_ashr_i32 s65, s2, 8
	s_bfe_u32 s64, s2, 0x20006
	v_and_b32_e32 v230, 15, v128
	v_bfe_u32 v229, v128, 4, 2
	s_mov_b64 s[26:27], 0
	s_cmp_lt_i32 s66, 2
	s_mov_b64 s[2:3], 0
	s_cbranch_scc1 .LBB0_480
	s_cmp_gt_i32 s66, 3
	s_cbranch_scc0 .LBB0_444
	s_cmp_gt_i32 s66, 4
	s_cbranch_scc0 .LBB0_375
	s_cmp_eq_u32 s66, 5
	s_mov_b64 s[2:3], -1
	s_cbranch_scc0 .LBB0_374
	v_mov_b32_e32 v128, 0x20810
	ds_read_b128 v[128:131], v128
	v_mov_b32_e32 v132, 0x20820
	ds_read_b128 v[132:135], v132
	v_mov_b32_e32 v136, 0x20830
	ds_read_b128 v[136:139], v136
	v_mov_b32_e32 v140, 0x20860
	ds_read_b128 v[140:143], v140
	v_mov_b32_e32 v144, 0x20870
	ds_read_b128 v[144:147], v144
	v_mov_b32_e32 v148, 0x20850
	ds_read_b128 v[148:151], v148
	v_mov_b32_e32 v152, 0x20808
	ds_read_b32 v152, v152
	s_waitcnt lgkmcnt(0)
	v_readfirstlane_b32 s38, v128
	v_readfirstlane_b32 s39, v129
	v_readfirstlane_b32 s34, v134
	v_readfirstlane_b32 s35, v135
	v_readfirstlane_b32 s40, v136
	v_readfirstlane_b32 s41, v137
	v_readfirstlane_b32 s26, v140
	v_readfirstlane_b32 s27, v141
	v_readfirstlane_b32 s28, v142
	v_readfirstlane_b32 s29, v143
	v_readfirstlane_b32 s30, v144
	v_readfirstlane_b32 s31, v145
	v_readfirstlane_b32 s36, v152
	v_readfirstlane_b32 s2, v148
	v_readfirstlane_b32 s3, v149
	v_readfirstlane_b32 s10, v150
	v_readfirstlane_b32 s11, v151
	v_mov_b32_e32 v212, 0
	v_mov_b32_e32 v213, 0
	v_mov_b32_e32 v214, 0
	v_mov_b32_e32 v215, 0
	v_mov_b32_e32 v172, 0
	v_mov_b32_e32 v173, 0
	v_mov_b32_e32 v174, 0
	v_mov_b32_e32 v175, 0
	s_lshl_b32 s8, s63, 8
	s_lshl_b32 s9, s65, 6
	s_add_i32 s8, s8, s9
	v_or_b32_e32 v231, s8, v230
	s_lshl_b32 s9, s62, 8
	s_lshl_b32 s8, s64, 5
	s_or_b32 s9, s9, s8
	v_lshl_or_b32 v176, v229, 3, s9
	v_lshlrev_b32_e32 v128, 2, v231
	global_load_dword v204, v128, s[2:3]
	global_load_dword v205, v128, s[2:3] offset:64
	global_load_dword v206, v128, s[2:3] offset:128
	global_load_dword v207, v128, s[2:3] offset:192
	global_load_dword v208, v128, s[2:3] offset:512
	global_load_dword v209, v128, s[2:3] offset:576
	global_load_dword v210, v128, s[2:3] offset:640
	global_load_dword v211, v128, s[2:3] offset:704
	v_lshl_add_u32 v248, v231, 10, v176
	v_lshlrev_b32_e32 v249, 1, v248
	v_lshlrev_b32_e32 v248, 2, v248
	s_bfe_u32 s37, s63, 0x130005
	s_mulk_i32 s37, 0x2400
	v_add_u32_e32 v231, s37, v176
	v_lshlrev_b32_e32 v231, 2, v231
	v_lshlrev_b32_e32 v176, 2, v176
	s_waitcnt vmcnt(0)
	v_fmamk_f32 v204, v204, 0x3a800000, v222
	v_fmamk_f32 v205, v205, 0x3a800000, v222
	v_fmamk_f32 v206, v206, 0x3a800000, v222
	v_fmamk_f32 v207, v207, 0x3a800000, v222
	v_fmamk_f32 v208, v208, 0x3a800000, v222
	v_fmamk_f32 v209, v209, 0x3a800000, v222
	v_fmamk_f32 v210, v210, 0x3a800000, v222
	v_fmamk_f32 v211, v211, 0x3a800000, v222
	v_rsq_f32_e32 v204, v204
	v_rsq_f32_e32 v205, v205
	v_rsq_f32_e32 v206, v206
	v_rsq_f32_e32 v207, v207
	v_rsq_f32_e32 v208, v208
	v_rsq_f32_e32 v209, v209
	v_rsq_f32_e32 v210, v210
	v_rsq_f32_e32 v211, v211
	global_load_dwordx4 v[232:235], v231, s[40:41] offset:0
	global_load_dwordx4 v[236:239], v231, s[40:41] offset:16
	global_load_dwordx4 v[240:243], v176, s[28:29] offset:0
	global_load_dwordx4 v[244:247], v176, s[28:29] offset:16
	global_load_dwordx4 v[188:191], v231, s[30:31] offset:0
	global_load_dwordx4 v[192:195], v231, s[30:31] offset:16
	global_load_dwordx4 v[196:199], v176, s[10:11] offset:0
	global_load_dwordx4 v[200:203], v176, s[10:11] offset:16
	s_mov_b64 s[8:9], s[34:35]
	global_load_dwordx4 v[128:131], v248, s[8:9] offset:0
	global_load_dwordx4 v[132:135], v248, s[8:9] offset:16
	s_add_u32 s8, s34, 0x10000
	s_addc_u32 s9, s35, 0
	global_load_dwordx4 v[136:139], v248, s[8:9] offset:0
	global_load_dwordx4 v[140:143], v248, s[8:9] offset:16
	s_add_u32 s8, s34, 0x20000
	s_addc_u32 s9, s35, 0
	global_load_dwordx4 v[144:147], v248, s[8:9] offset:0
	global_load_dwordx4 v[148:151], v248, s[8:9] offset:16
	s_add_u32 s8, s34, 0x30000
	s_addc_u32 s9, s35, 0
	global_load_dwordx4 v[152:155], v248, s[8:9] offset:0
	global_load_dwordx4 v[156:159], v248, s[8:9] offset:16
	s_add_u32 s8, s34, 0x80000
	s_addc_u32 s9, s35, 0
	global_load_dwordx4 v[180:183], v248, s[8:9] offset:0
	global_load_dwordx4 v[184:187], v248, s[8:9] offset:16
	s_waitcnt vmcnt(10)
	v_pk_mul_f32 v[232:233], s[36:37], v[232:233] op_sel_hi:[0,1]
	v_pk_mul_f32 v[234:235], s[36:37], v[234:235] op_sel_hi:[0,1]
	v_pk_mul_f32 v[236:237], s[36:37], v[236:237] op_sel_hi:[0,1]
	v_pk_mul_f32 v[238:239], s[36:37], v[238:239] op_sel_hi:[0,1]
	v_pk_add_f32 v[188:189], v[188:189], 1.0 op_sel_hi:[1,0]
	v_pk_add_f32 v[190:191], v[190:191], 1.0 op_sel_hi:[1,0]
	v_pk_add_f32 v[192:193], v[192:193], 1.0 op_sel_hi:[1,0]
	v_pk_add_f32 v[194:195], v[194:195], 1.0 op_sel_hi:[1,0]
	v_pk_mul_f32 v[240:241], v[240:241], v[188:189]
	v_pk_mul_f32 v[242:243], v[242:243], v[190:191]
	v_pk_mul_f32 v[244:245], v[244:245], v[192:193]
	v_pk_mul_f32 v[246:247], v[246:247], v[194:195]
	s_add_u32 s8, s34, 0x90000
	s_addc_u32 s9, s35, 0
	global_load_dwordx4 v[188:191], v248, s[8:9] offset:0
	global_load_dwordx4 v[192:195], v248, s[8:9] offset:16
	s_mov_b64 s[42:43], s[38:39]
	s_mov_b64 s[2:3], s[26:27]
	s_waitcnt vmcnt(10)
; __device__ __forceinline__ unsigned cvt_pk_bf16(float lo, float hi) { unsigned r; asm volatile("v_cvt_pk_bf16_f32 %0, %1, %2" : "=v"(r) : "v"(lo), "v"(hi)); return r; }
;     static __device__ __forceinline__ void run(const f32x4 (&acc)[2][2][4][2], const Unit& u, int wr, int wc, int fr, int fq, const float* xin, float* xout, const float* gate, float gs, const float* lazy_ssq, const float* lazy_g, ...
;     ...
;                 for (int j = 0; j < 2; ++j) { const int i_ = 2 * pp + j, ai = i_ >> 2, m = i_ & 3; const unsigned off = (row0 + ai * HALF + m * 16) * 1024u + col;
;                     const f32x4 xi0 = xq[pp & 1][j][0], xi1 = xq[pp & 1][j][1];
;                     f32x4 xo0 = gv[0] * acc[ai][bj][m][0], xo1 = gv[1] * acc[ai][bj][m][1];
;                     if (LAZY) { xo0 = xo0 + xi0 * lg[0] * rl[ai][m]; xo1 = xo1 + xi1 * lg[1] * rl[ai][m]; } else { xo0 = xo0 + xi0; xo1 = xo1 + xi1; }
;                     *(f32x4*)(xout + off) = xo0; *(f32x4*)(xout + off + 4) = xo1;
;                     if (aout) { const f32x4 a0 = xo0 * wv[0], a1 = xo1 * wv[1]; u32x4 w; w.x = cvt_pk_bf16(a0[0], a0[1]); w.y = cvt_pk_bf16(a0[2], a0[3]); w.z = cvt_pk_bf16(a1[0], a1[1]); w.w = cvt_pk_bf16(a1[2], a1[3]);
;                         *(u32x4*)(aout + off) = w;
;                         sq[ai][m] += ((xo0[0] * xo0[0] + xo0[1] * xo0[1]) + (xo0[2] * xo0[2] + xo0[3] * xo0[3])) + ((xo1[0] * xo1[0] + xo1[1] * xo1[1]) + (xo1[2] * xo1[2] + xo1[3] * xo1[3]));
	v_pk_mul_f32 v[128:129], v[128:129], v[196:197]
	v_pk_mul_f32 v[130:131], v[130:131], v[198:199]
	v_pk_mul_f32 v[132:133], v[132:133], v[200:201]
	v_pk_mul_f32 v[134:135], v[134:135], v[202:203]
	v_mul_f32_e32 v128, v128, v204
	v_mul_f32_e32 v129, v129, v204
	v_mul_f32_e32 v130, v130, v204
	v_mul_f32_e32 v131, v131, v204
	v_mul_f32_e32 v132, v132, v204
	v_mul_f32_e32 v133, v133, v204
	v_mul_f32_e32 v134, v134, v204
	v_mul_f32_e32 v135, v135, v204
	v_pk_fma_f32 v[124:125], v[232:233], v[124:125], v[128:129]
	v_pk_fma_f32 v[126:127], v[234:235], v[126:127], v[130:131]
	v_pk_fma_f32 v[120:121], v[236:237], v[120:121], v[132:133]
	v_pk_fma_f32 v[122:123], v[238:239], v[122:123], v[134:135]
	global_store_dwordx4 v248, v[124:127], s[42:43] offset:0
	global_store_dwordx4 v248, v[120:123], s[42:43] offset:16
	v_pk_mul_f32 v[128:129], v[124:125], v[240:241]
	v_pk_mul_f32 v[130:131], v[126:127], v[242:243]
	v_pk_mul_f32 v[132:133], v[120:121], v[244:245]
	v_pk_mul_f32 v[134:135], v[122:123], v[246:247]
	v_cvt_pk_bf16_f32 v128, v128, v129
	v_cvt_pk_bf16_f32 v129, v130, v131
	v_cvt_pk_bf16_f32 v130, v132, v133
	v_cvt_pk_bf16_f32 v131, v134, v135
	global_store_dwordx4 v249, v[128:131], s[2:3] offset:0
	v_mul_f32_e32 v132, v125, v125
	v_mul_f32_e32 v133, v127, v127
	v_mul_f32_e32 v134, v121, v121
	v_mul_f32_e32 v135, v123, v123
	v_fmac_f32_e32 v132, v124, v124
	v_fmac_f32_e32 v133, v126, v126
	v_fmac_f32_e32 v134, v120, v120
	v_fmac_f32_e32 v135, v122, v122
	v_add_f32_e32 v132, v132, v133
	v_add_f32_e32 v134, v134, v135
	v_add_f32_e32 v132, v132, v134
	v_add_f32_e32 v212, v212, v132
	s_add_u32 s8, s34, 0xa0000
	s_addc_u32 s9, s35, 0
	global_load_dwordx4 v[128:131], v248, s[8:9] offset:0
	global_load_dwordx4 v[132:135], v248, s[8:9] offset:16
	s_add_u32 s42, s38, 0x10000
	s_addc_u32 s43, s39, 0
	s_add_u32 s2, s26, 0x8000
	s_addc_u32 s3, s27, 0
	s_waitcnt vmcnt(13)
	v_pk_mul_f32 v[136:137], v[136:137], v[196:197]
	v_pk_mul_f32 v[138:139], v[138:139], v[198:199]
	v_pk_mul_f32 v[140:141], v[140:141], v[200:201]
	v_pk_mul_f32 v[142:143], v[142:143], v[202:203]
	v_mul_f32_e32 v136, v136, v205
	v_mul_f32_e32 v137, v137, v205
	v_mul_f32_e32 v138, v138, v205
	v_mul_f32_e32 v139, v139, v205
	v_mul_f32_e32 v140, v140, v205
	v_mul_f32_e32 v141, v141, v205
	v_mul_f32_e32 v142, v142, v205
	v_mul_f32_e32 v143, v143, v205
	v_pk_fma_f32 v[108:109], v[232:233], v[108:109], v[136:137]
	v_pk_fma_f32 v[110:111], v[234:235], v[110:111], v[138:139]
	v_pk_fma_f32 v[104:105], v[236:237], v[104:105], v[140:141]
	v_pk_fma_f32 v[106:107], v[238:239], v[106:107], v[142:143]
	global_store_dwordx4 v248, v[108:111], s[42:43] offset:0
	global_store_dwordx4 v248, v[104:107], s[42:43] offset:16
	v_pk_mul_f32 v[136:137], v[108:109], v[240:241]
	v_pk_mul_f32 v[138:139], v[110:111], v[242:243]
	v_pk_mul_f32 v[140:141], v[104:105], v[244:245]
	v_pk_mul_f32 v[142:143], v[106:107], v[246:247]
	v_cvt_pk_bf16_f32 v136, v136, v137
	v_cvt_pk_bf16_f32 v137, v138, v139
	v_cvt_pk_bf16_f32 v138, v140, v141
	v_cvt_pk_bf16_f32 v139, v142, v143
	global_store_dwordx4 v249, v[136:139], s[2:3] offset:0
	v_mul_f32_e32 v140, v109, v109
	v_mul_f32_e32 v141, v111, v111
	v_mul_f32_e32 v142, v105, v105
	v_mul_f32_e32 v143, v107, v107
	v_fmac_f32_e32 v140, v108, v108
	v_fmac_f32_e32 v141, v110, v110
	v_fmac_f32_e32 v142, v104, v104
	v_fmac_f32_e32 v143, v106, v106
	v_add_f32_e32 v140, v140, v141
	v_add_f32_e32 v142, v142, v143
	v_add_f32_e32 v140, v140, v142
	v_add_f32_e32 v213, v213, v140
	s_add_u32 s8, s34, 0xb0000
	s_addc_u32 s9, s35, 0
	global_load_dwordx4 v[136:139], v248, s[8:9] offset:0
	global_load_dwordx4 v[140:143], v248, s[8:9] offset:16
	s_add_u32 s42, s38, 0x20000
	s_addc_u32 s43, s39, 0
	s_add_u32 s2, s26, 0x10000
	s_addc_u32 s3, s27, 0
	s_waitcnt vmcnt(16)
	v_pk_mul_f32 v[144:145], v[144:145], v[196:197]
	v_pk_mul_f32 v[146:147], v[146:147], v[198:199]
	v_pk_mul_f32 v[148:149], v[148:149], v[200:201]
	v_pk_mul_f32 v[150:151], v[150:151], v[202:203]
	v_mul_f32_e32 v144, v144, v206
	v_mul_f32_e32 v145, v145, v206
	v_mul_f32_e32 v146, v146, v206
	v_mul_f32_e32 v147, v147, v206
	v_mul_f32_e32 v148, v148, v206
	v_mul_f32_e32 v149, v149, v206
	v_mul_f32_e32 v150, v150, v206
	v_mul_f32_e32 v151, v151, v206
	v_pk_fma_f32 v[92:93], v[232:233], v[92:93], v[144:145]
	v_pk_fma_f32 v[94:95], v[234:235], v[94:95], v[146:147]
	v_pk_fma_f32 v[88:89], v[236:237], v[88:89], v[148:149]
	v_pk_fma_f32 v[90:91], v[238:239], v[90:91], v[150:151]
	global_store_dwordx4 v248, v[92:95], s[42:43] offset:0
	global_store_dwordx4 v248, v[88:91], s[42:43] offset:16
	v_pk_mul_f32 v[144:145], v[92:93], v[240:241]
	v_pk_mul_f32 v[146:147], v[94:95], v[242:243]
	v_pk_mul_f32 v[148:149], v[88:89], v[244:245]
	v_pk_mul_f32 v[150:151], v[90:91], v[246:247]
	v_cvt_pk_bf16_f32 v144, v144, v145
	v_cvt_pk_bf16_f32 v145, v146, v147
	v_cvt_pk_bf16_f32 v146, v148, v149
	v_cvt_pk_bf16_f32 v147, v150, v151
	global_store_dwordx4 v249, v[144:147], s[2:3] offset:0
	v_mul_f32_e32 v148, v93, v93
	v_mul_f32_e32 v149, v95, v95
	v_mul_f32_e32 v150, v89, v89
	v_mul_f32_e32 v151, v91, v91
	v_fmac_f32_e32 v148, v92, v92
	v_fmac_f32_e32 v149, v94, v94
	v_fmac_f32_e32 v150, v88, v88
	v_fmac_f32_e32 v151, v90, v90
	v_add_f32_e32 v148, v148, v149
	v_add_f32_e32 v150, v150, v151
	v_add_f32_e32 v148, v148, v150
	v_add_f32_e32 v214, v214, v148
	s_add_u32 s42, s38, 0x30000
	s_addc_u32 s43, s39, 0
	s_add_u32 s2, s26, 0x18000
	s_addc_u32 s3, s27, 0
	s_waitcnt vmcnt(17)
; __device__ __forceinline__ unsigned cvt_pk_bf16(float lo, float hi) { unsigned r; asm volatile("v_cvt_pk_bf16_f32 %0, %1, %2" : "=v"(r) : "v"(lo), "v"(hi)); return r; }
;     static __device__ __forceinline__ void run(const f32x4 (&acc)[2][2][4][2], const Unit& u, int wr, int wc, int fr, int fq, const float* xin, float* xout, const float* gate, float gs, const float* lazy_ssq, const float* lazy_g, ...
;     ...
;                 for (int j = 0; j < 2; ++j) { const int i_ = 2 * pp + j, ai = i_ >> 2, m = i_ & 3; const unsigned off = (row0 + ai * HALF + m * 16) * 1024u + col;
;                     const f32x4 xi0 = xq[pp & 1][j][0], xi1 = xq[pp & 1][j][1];
;                     f32x4 xo0 = gv[0] * acc[ai][bj][m][0], xo1 = gv[1] * acc[ai][bj][m][1];
;                     if (LAZY) { xo0 = xo0 + xi0 * lg[0] * rl[ai][m]; xo1 = xo1 + xi1 * lg[1] * rl[ai][m]; } else { xo0 = xo0 + xi0; xo1 = xo1 + xi1; }
;                     *(f32x4*)(xout + off) = xo0; *(f32x4*)(xout + off + 4) = xo1;
;                     if (aout) { const f32x4 a0 = xo0 * wv[0], a1 = xo1 * wv[1]; u32x4 w; w.x = cvt_pk_bf16(a0[0], a0[1]); w.y = cvt_pk_bf16(a0[2], a0[3]); w.z = cvt_pk_bf16(a1[0], a1[1]); w.w = cvt_pk_bf16(a1[2], a1[3]);
;                         *(u32x4*)(aout + off) = w;
;                         sq[ai][m] += ((xo0[0] * xo0[0] + xo0[1] * xo0[1]) + (xo0[2] * xo0[2] + xo0[3] * xo0[3])) + ((xo1[0] * xo1[0] + xo1[1] * xo1[1]) + (xo1[2] * xo1[2] + xo1[3] * xo1[3]));
	v_pk_mul_f32 v[152:153], v[152:153], v[196:197]
	v_pk_mul_f32 v[154:155], v[154:155], v[198:199]
	v_pk_mul_f32 v[156:157], v[156:157], v[200:201]
	v_pk_mul_f32 v[158:159], v[158:159], v[202:203]
	v_mul_f32_e32 v152, v152, v207
	v_mul_f32_e32 v153, v153, v207
	v_mul_f32_e32 v154, v154, v207
	v_mul_f32_e32 v155, v155, v207
	v_mul_f32_e32 v156, v156, v207
	v_mul_f32_e32 v157, v157, v207
	v_mul_f32_e32 v158, v158, v207
	v_mul_f32_e32 v159, v159, v207
	v_pk_fma_f32 v[76:77], v[232:233], v[76:77], v[152:153]
	v_pk_fma_f32 v[78:79], v[234:235], v[78:79], v[154:155]
	v_pk_fma_f32 v[72:73], v[236:237], v[72:73], v[156:157]
	v_pk_fma_f32 v[74:75], v[238:239], v[74:75], v[158:159]
	global_store_dwordx4 v248, v[76:79], s[42:43] offset:0
	global_store_dwordx4 v248, v[72:75], s[42:43] offset:16
	v_pk_mul_f32 v[152:153], v[76:77], v[240:241]
	v_pk_mul_f32 v[154:155], v[78:79], v[242:243]
	v_pk_mul_f32 v[156:157], v[72:73], v[244:245]
	v_pk_mul_f32 v[158:159], v[74:75], v[246:247]
	v_cvt_pk_bf16_f32 v152, v152, v153
	v_cvt_pk_bf16_f32 v153, v154, v155
	v_cvt_pk_bf16_f32 v154, v156, v157
	v_cvt_pk_bf16_f32 v155, v158, v159
	global_store_dwordx4 v249, v[152:155], s[2:3] offset:0
	v_mul_f32_e32 v156, v77, v77
	v_mul_f32_e32 v157, v79, v79
	v_mul_f32_e32 v158, v73, v73
	v_mul_f32_e32 v159, v75, v75
	v_fmac_f32_e32 v156, v76, v76
	v_fmac_f32_e32 v157, v78, v78
	v_fmac_f32_e32 v158, v72, v72
	v_fmac_f32_e32 v159, v74, v74
	v_add_f32_e32 v156, v156, v157
	v_add_f32_e32 v158, v158, v159
	v_add_f32_e32 v156, v156, v158
	v_add_f32_e32 v215, v215, v156
	s_add_u32 s42, s38, 0x80000
	s_addc_u32 s43, s39, 0
	s_add_u32 s2, s26, 0x40000
	s_addc_u32 s3, s27, 0
	s_waitcnt vmcnt(18)
	v_pk_mul_f32 v[180:181], v[180:181], v[196:197]
	v_pk_mul_f32 v[182:183], v[182:183], v[198:199]
	v_pk_mul_f32 v[184:185], v[184:185], v[200:201]
	v_pk_mul_f32 v[186:187], v[186:187], v[202:203]
	v_mul_f32_e32 v180, v180, v208
	v_mul_f32_e32 v181, v181, v208
	v_mul_f32_e32 v182, v182, v208
	v_mul_f32_e32 v183, v183, v208
	v_mul_f32_e32 v184, v184, v208
	v_mul_f32_e32 v185, v185, v208
	v_mul_f32_e32 v186, v186, v208
	v_mul_f32_e32 v187, v187, v208
	v_pk_fma_f32 v[60:61], v[232:233], v[60:61], v[180:181]
	v_pk_fma_f32 v[62:63], v[234:235], v[62:63], v[182:183]
	v_pk_fma_f32 v[56:57], v[236:237], v[56:57], v[184:185]
	v_pk_fma_f32 v[58:59], v[238:239], v[58:59], v[186:187]
	global_store_dwordx4 v248, v[60:63], s[42:43] offset:0
	global_store_dwordx4 v248, v[56:59], s[42:43] offset:16
	v_pk_mul_f32 v[180:181], v[60:61], v[240:241]
	v_pk_mul_f32 v[182:183], v[62:63], v[242:243]
	v_pk_mul_f32 v[184:185], v[56:57], v[244:245]
	v_pk_mul_f32 v[186:187], v[58:59], v[246:247]
	v_cvt_pk_bf16_f32 v180, v180, v181
	v_cvt_pk_bf16_f32 v181, v182, v183
	v_cvt_pk_bf16_f32 v182, v184, v185
	v_cvt_pk_bf16_f32 v183, v186, v187
	global_store_dwordx4 v249, v[180:183], s[2:3] offset:0
	v_mul_f32_e32 v184, v61, v61
	v_mul_f32_e32 v185, v63, v63
	v_mul_f32_e32 v186, v57, v57
	v_mul_f32_e32 v187, v59, v59
	v_fmac_f32_e32 v184, v60, v60
	v_fmac_f32_e32 v185, v62, v62
	v_fmac_f32_e32 v186, v56, v56
	v_fmac_f32_e32 v187, v58, v58
	v_add_f32_e32 v184, v184, v185
	v_add_f32_e32 v186, v186, v187
	v_add_f32_e32 v184, v184, v186
	v_add_f32_e32 v172, v172, v184
	s_add_u32 s42, s38, 0x90000
	s_addc_u32 s43, s39, 0
	s_add_u32 s2, s26, 0x48000
	s_addc_u32 s3, s27, 0
	s_waitcnt vmcnt(19)
	v_pk_mul_f32 v[188:189], v[188:189], v[196:197]
	v_pk_mul_f32 v[190:191], v[190:191], v[198:199]
	v_pk_mul_f32 v[192:193], v[192:193], v[200:201]
	v_pk_mul_f32 v[194:195], v[194:195], v[202:203]
	v_mul_f32_e32 v188, v188, v209
	v_mul_f32_e32 v189, v189, v209
	v_mul_f32_e32 v190, v190, v209
	v_mul_f32_e32 v191, v191, v209
	v_mul_f32_e32 v192, v192, v209
	v_mul_f32_e32 v193, v193, v209
	v_mul_f32_e32 v194, v194, v209
	v_mul_f32_e32 v195, v195, v209
	v_pk_fma_f32 v[44:45], v[232:233], v[44:45], v[188:189]
	v_pk_fma_f32 v[46:47], v[234:235], v[46:47], v[190:191]
	v_pk_fma_f32 v[40:41], v[236:237], v[40:41], v[192:193]
	v_pk_fma_f32 v[42:43], v[238:239], v[42:43], v[194:195]
	global_store_dwordx4 v248, v[44:47], s[42:43] offset:0
	global_store_dwordx4 v248, v[40:43], s[42:43] offset:16
	v_pk_mul_f32 v[188:189], v[44:45], v[240:241]
	v_pk_mul_f32 v[190:191], v[46:47], v[242:243]
	v_pk_mul_f32 v[192:193], v[40:41], v[244:245]
	v_pk_mul_f32 v[194:195], v[42:43], v[246:247]
	v_cvt_pk_bf16_f32 v188, v188, v189
	v_cvt_pk_bf16_f32 v189, v190, v191
	v_cvt_pk_bf16_f32 v190, v192, v193
	v_cvt_pk_bf16_f32 v191, v194, v195
	global_store_dwordx4 v249, v[188:191], s[2:3] offset:0
	v_mul_f32_e32 v192, v45, v45
	v_mul_f32_e32 v193, v47, v47
	v_mul_f32_e32 v194, v41, v41
	v_mul_f32_e32 v195, v43, v43
	v_fmac_f32_e32 v192, v44, v44
	v_fmac_f32_e32 v193, v46, v46
	v_fmac_f32_e32 v194, v40, v40
	v_fmac_f32_e32 v195, v42, v42
	v_add_f32_e32 v192, v192, v193
	v_add_f32_e32 v194, v194, v195
	v_add_f32_e32 v192, v192, v194
	v_add_f32_e32 v173, v173, v192
	s_add_u32 s42, s38, 0xa0000
	s_addc_u32 s43, s39, 0
	s_add_u32 s2, s26, 0x50000
	s_addc_u32 s3, s27, 0
	s_waitcnt vmcnt(17)
;     static __device__ __forceinline__ void run(const f32x4 (&acc)[2][2][4][2], const Unit& u, int wr, int wc, int fr, int fq, const float* xin, float* xout, const float* gate, float gs, const float* lazy_ssq, const float* lazy_g, ...
;     ...
;         for (int bj = 0; bj < 2; ++bj) {
;             const unsigned col = col0 + bj * HALF;
;             f32x4 gv[2], lg[2], wv[2], w2[2];
; #pragma unroll
;             for (int n = 0; n < 2; ++n) {
;                 gv[n] = *(const f32x4*)(gate + (b * 9216u + col + 4 * n)) * gs;
;                 lg[n] = (f32x4){1.f, 1.f, 1.f, 1.f}; if (LAZY) lg[n] = *(const f32x4*)(lazy_g + col + 4 * n);
;                 wv[n] = (f32x4){0.f, 0.f, 0.f, 0.f}; w2[n] = (f32x4){1.f, 1.f, 1.f, 1.f};
;                 if (aout) { wv[n] = *(const f32x4*)(wg + col + 4 * n) * (*(const f32x4*)(wsc + (b * 9216u + col + 4 * n)) + 1.0f); if (WG2) { w2[n] = *(const f32x4*)(wg2 + col + 4 * n); wv[n] = wv[n] * w2[n]; } }
;             }
;             f32x4 xq[2][2][2];
;     ...
;             constexpr bool DEEP = !LAZY && !WG2;
;             if (DEEP) RES_LD(0, 0);
; #pragma unroll
;             for (int pp = 0; pp < 4; ++pp) {
;                 if (DEEP) { if (pp < 3) RES_LD((pp + 1) & 1, pp + 1); } else RES_LD(pp & 1, pp);
; #pragma unroll
;                 for (int j = 0; j < 2; ++j) { const int i_ = 2 * pp + j, ai = i_ >> 2, m = i_ & 3; const unsigned off = (row0 + ai * HALF + m * 16) * 1024u + col;
;                     const f32x4 xi0 = xq[pp & 1][j][0], xi1 = xq[pp & 1][j][1];
;                     f32x4 xo0 = gv[0] * acc[ai][bj][m][0], xo1 = gv[1] * acc[ai][bj][m][1];
;                     if (LAZY) { xo0 = xo0 + xi0 * lg[0] * rl[ai][m]; xo1 = xo1 + xi1 * lg[1] * rl[ai][m]; } else { xo0 = xo0 + xi0; xo1 = xo1 + xi1; }
;                     *(f32x4*)(xout + off) = xo0; *(f32x4*)(xout + off + 4) = xo1;
;                     if (aout) { const f32x4 a0 = xo0 * wv[0], a1 = xo1 * wv[1]; u32x4 w; w.x = cvt_pk_bf16(a0[0], a0[1]); w.y = cvt_pk_bf16(a0[2], a0[3]); w.z = cvt_pk_bf16(a1[0], a1[1]); w.w = cvt_pk_bf16(a1[2], a1[3]);
;                         *(u32x4*)(aout + off) = w;
;                         sq[ai][m] += ((xo0[0] * xo0[0] + xo0[1] * xo0[1]) + (xo0[2] * xo0[2] + xo0[3] * xo0[3])) + ((xo1[0] * xo1[0] + xo1[1] * xo1[1]) + (xo1[2] * xo1[2] + xo1[3] * xo1[3]));
	v_pk_mul_f32 v[128:129], v[128:129], v[196:197]
	v_pk_mul_f32 v[130:131], v[130:131], v[198:199]
	v_pk_mul_f32 v[132:133], v[132:133], v[200:201]
	v_pk_mul_f32 v[134:135], v[134:135], v[202:203]
	v_mul_f32_e32 v128, v128, v210
	v_mul_f32_e32 v129, v129, v210
	v_mul_f32_e32 v130, v130, v210
	v_mul_f32_e32 v131, v131, v210
	v_mul_f32_e32 v132, v132, v210
	v_mul_f32_e32 v133, v133, v210
	v_mul_f32_e32 v134, v134, v210
	v_mul_f32_e32 v135, v135, v210
	v_pk_fma_f32 v[28:29], v[232:233], v[28:29], v[128:129]
	v_pk_fma_f32 v[30:31], v[234:235], v[30:31], v[130:131]
	v_pk_fma_f32 v[24:25], v[236:237], v[24:25], v[132:133]
	v_pk_fma_f32 v[26:27], v[238:239], v[26:27], v[134:135]
	global_store_dwordx4 v248, v[28:31], s[42:43] offset:0
	global_store_dwordx4 v248, v[24:27], s[42:43] offset:16
	v_pk_mul_f32 v[128:129], v[28:29], v[240:241]
	v_pk_mul_f32 v[130:131], v[30:31], v[242:243]
	v_pk_mul_f32 v[132:133], v[24:25], v[244:245]
	v_pk_mul_f32 v[134:135], v[26:27], v[246:247]
	v_cvt_pk_bf16_f32 v128, v128, v129
	v_cvt_pk_bf16_f32 v129, v130, v131
	v_cvt_pk_bf16_f32 v130, v132, v133
	v_cvt_pk_bf16_f32 v131, v134, v135
	global_store_dwordx4 v249, v[128:131], s[2:3] offset:0
	v_mul_f32_e32 v132, v29, v29
	v_mul_f32_e32 v133, v31, v31
	v_mul_f32_e32 v134, v25, v25
	v_mul_f32_e32 v135, v27, v27
	v_fmac_f32_e32 v132, v28, v28
	v_fmac_f32_e32 v133, v30, v30
	v_fmac_f32_e32 v134, v24, v24
	v_fmac_f32_e32 v135, v26, v26
	v_add_f32_e32 v132, v132, v133
	v_add_f32_e32 v134, v134, v135
	v_add_f32_e32 v132, v132, v134
	v_add_f32_e32 v174, v174, v132
	s_add_u32 s42, s38, 0xb0000
	s_addc_u32 s43, s39, 0
	s_add_u32 s2, s26, 0x58000
	s_addc_u32 s3, s27, 0
	s_waitcnt vmcnt(15)
	v_pk_mul_f32 v[136:137], v[136:137], v[196:197]
	v_pk_mul_f32 v[138:139], v[138:139], v[198:199]
	v_pk_mul_f32 v[140:141], v[140:141], v[200:201]
	v_pk_mul_f32 v[142:143], v[142:143], v[202:203]
	v_mul_f32_e32 v136, v136, v211
	v_mul_f32_e32 v137, v137, v211
	v_mul_f32_e32 v138, v138, v211
	v_mul_f32_e32 v139, v139, v211
	v_mul_f32_e32 v140, v140, v211
	v_mul_f32_e32 v141, v141, v211
	v_mul_f32_e32 v142, v142, v211
	v_mul_f32_e32 v143, v143, v211
	v_pk_fma_f32 v[12:13], v[232:233], v[12:13], v[136:137]
	v_pk_fma_f32 v[14:15], v[234:235], v[14:15], v[138:139]
	v_pk_fma_f32 v[8:9], v[236:237], v[8:9], v[140:141]
	v_pk_fma_f32 v[10:11], v[238:239], v[10:11], v[142:143]
	global_store_dwordx4 v248, v[12:15], s[42:43] offset:0
	global_store_dwordx4 v248, v[8:11], s[42:43] offset:16
	v_pk_mul_f32 v[136:137], v[12:13], v[240:241]
	v_pk_mul_f32 v[138:139], v[14:15], v[242:243]
	v_pk_mul_f32 v[140:141], v[8:9], v[244:245]
	v_pk_mul_f32 v[142:143], v[10:11], v[246:247]
	v_cvt_pk_bf16_f32 v136, v136, v137
	v_cvt_pk_bf16_f32 v137, v138, v139
	v_cvt_pk_bf16_f32 v138, v140, v141
	v_cvt_pk_bf16_f32 v139, v142, v143
	global_store_dwordx4 v249, v[136:139], s[2:3] offset:0
	v_mul_f32_e32 v140, v13, v13
	v_mul_f32_e32 v141, v15, v15
	v_mul_f32_e32 v142, v9, v9
	v_mul_f32_e32 v143, v11, v11
	v_fmac_f32_e32 v140, v12, v12
	v_fmac_f32_e32 v141, v14, v14
	v_fmac_f32_e32 v142, v8, v8
	v_fmac_f32_e32 v143, v10, v10
	v_add_f32_e32 v140, v140, v141
	v_add_f32_e32 v142, v142, v143
	v_add_f32_e32 v140, v140, v142
	v_add_f32_e32 v175, v175, v140
	global_load_dwordx4 v[232:235], v231, s[40:41] offset:512
	global_load_dwordx4 v[236:239], v231, s[40:41] offset:528
	global_load_dwordx4 v[240:243], v176, s[28:29] offset:512
	global_load_dwordx4 v[244:247], v176, s[28:29] offset:528
	global_load_dwordx4 v[188:191], v231, s[30:31] offset:512
	global_load_dwordx4 v[192:195], v231, s[30:31] offset:528
	global_load_dwordx4 v[196:199], v176, s[10:11] offset:512
	global_load_dwordx4 v[200:203], v176, s[10:11] offset:528
	s_mov_b64 s[8:9], s[34:35]
	global_load_dwordx4 v[128:131], v248, s[8:9] offset:512
	global_load_dwordx4 v[132:135], v248, s[8:9] offset:528
	s_add_u32 s8, s34, 0x10000
	s_addc_u32 s9, s35, 0
	global_load_dwordx4 v[136:139], v248, s[8:9] offset:512
	global_load_dwordx4 v[140:143], v248, s[8:9] offset:528
	s_add_u32 s8, s34, 0x20000
	s_addc_u32 s9, s35, 0
	global_load_dwordx4 v[144:147], v248, s[8:9] offset:512
	global_load_dwordx4 v[148:151], v248, s[8:9] offset:528
	s_add_u32 s8, s34, 0x30000
	s_addc_u32 s9, s35, 0
	global_load_dwordx4 v[152:155], v248, s[8:9] offset:512
	global_load_dwordx4 v[156:159], v248, s[8:9] offset:528
	s_add_u32 s8, s34, 0x80000
	s_addc_u32 s9, s35, 0
	global_load_dwordx4 v[180:183], v248, s[8:9] offset:512
	global_load_dwordx4 v[184:187], v248, s[8:9] offset:528
	s_waitcnt vmcnt(10)
	v_pk_mul_f32 v[232:233], s[36:37], v[232:233] op_sel_hi:[0,1]
	v_pk_mul_f32 v[234:235], s[36:37], v[234:235] op_sel_hi:[0,1]
	v_pk_mul_f32 v[236:237], s[36:37], v[236:237] op_sel_hi:[0,1]
	v_pk_mul_f32 v[238:239], s[36:37], v[238:239] op_sel_hi:[0,1]
	v_pk_add_f32 v[188:189], v[188:189], 1.0 op_sel_hi:[1,0]
	v_pk_add_f32 v[190:191], v[190:191], 1.0 op_sel_hi:[1,0]
	v_pk_add_f32 v[192:193], v[192:193], 1.0 op_sel_hi:[1,0]
	v_pk_add_f32 v[194:195], v[194:195], 1.0 op_sel_hi:[1,0]
	v_pk_mul_f32 v[240:241], v[240:241], v[188:189]
	v_pk_mul_f32 v[242:243], v[242:243], v[190:191]
	v_pk_mul_f32 v[244:245], v[244:245], v[192:193]
	v_pk_mul_f32 v[246:247], v[246:247], v[194:195]
	s_add_u32 s8, s34, 0x90000
	s_addc_u32 s9, s35, 0
	global_load_dwordx4 v[188:191], v248, s[8:9] offset:512
	global_load_dwordx4 v[192:195], v248, s[8:9] offset:528
	s_mov_b64 s[42:43], s[38:39]
	s_mov_b64 s[2:3], s[26:27]
	s_waitcnt vmcnt(10)
; __device__ __forceinline__ unsigned cvt_pk_bf16(float lo, float hi) { unsigned r; asm volatile("v_cvt_pk_bf16_f32 %0, %1, %2" : "=v"(r) : "v"(lo), "v"(hi)); return r; }
;     static __device__ __forceinline__ void run(const f32x4 (&acc)[2][2][4][2], const Unit& u, int wr, int wc, int fr, int fq, const float* xin, float* xout, const float* gate, float gs, const float* lazy_ssq, const float* lazy_g, ...
;     ...
;                 for (int j = 0; j < 2; ++j) { const int i_ = 2 * pp + j, ai = i_ >> 2, m = i_ & 3; const unsigned off = (row0 + ai * HALF + m * 16) * 1024u + col;
;                     const f32x4 xi0 = xq[pp & 1][j][0], xi1 = xq[pp & 1][j][1];
;                     f32x4 xo0 = gv[0] * acc[ai][bj][m][0], xo1 = gv[1] * acc[ai][bj][m][1];
;                     if (LAZY) { xo0 = xo0 + xi0 * lg[0] * rl[ai][m]; xo1 = xo1 + xi1 * lg[1] * rl[ai][m]; } else { xo0 = xo0 + xi0; xo1 = xo1 + xi1; }
;                     *(f32x4*)(xout + off) = xo0; *(f32x4*)(xout + off + 4) = xo1;
;                     if (aout) { const f32x4 a0 = xo0 * wv[0], a1 = xo1 * wv[1]; u32x4 w; w.x = cvt_pk_bf16(a0[0], a0[1]); w.y = cvt_pk_bf16(a0[2], a0[3]); w.z = cvt_pk_bf16(a1[0], a1[1]); w.w = cvt_pk_bf16(a1[2], a1[3]);
;                         *(u32x4*)(aout + off) = w;
;                         sq[ai][m] += ((xo0[0] * xo0[0] + xo0[1] * xo0[1]) + (xo0[2] * xo0[2] + xo0[3] * xo0[3])) + ((xo1[0] * xo1[0] + xo1[1] * xo1[1]) + (xo1[2] * xo1[2] + xo1[3] * xo1[3]));
	v_pk_mul_f32 v[128:129], v[128:129], v[196:197]
	v_pk_mul_f32 v[130:131], v[130:131], v[198:199]
	v_pk_mul_f32 v[132:133], v[132:133], v[200:201]
	v_pk_mul_f32 v[134:135], v[134:135], v[202:203]
	v_mul_f32_e32 v128, v128, v204
	v_mul_f32_e32 v129, v129, v204
	v_mul_f32_e32 v130, v130, v204
	v_mul_f32_e32 v131, v131, v204
	v_mul_f32_e32 v132, v132, v204
	v_mul_f32_e32 v133, v133, v204
	v_mul_f32_e32 v134, v134, v204
	v_mul_f32_e32 v135, v135, v204
	v_pk_fma_f32 v[116:117], v[232:233], v[116:117], v[128:129]
	v_pk_fma_f32 v[118:119], v[234:235], v[118:119], v[130:131]
	v_pk_fma_f32 v[112:113], v[236:237], v[112:113], v[132:133]
	v_pk_fma_f32 v[114:115], v[238:239], v[114:115], v[134:135]
	global_store_dwordx4 v248, v[116:119], s[42:43] offset:512
	global_store_dwordx4 v248, v[112:115], s[42:43] offset:528
	v_pk_mul_f32 v[128:129], v[116:117], v[240:241]
	v_pk_mul_f32 v[130:131], v[118:119], v[242:243]
	v_pk_mul_f32 v[132:133], v[112:113], v[244:245]
	v_pk_mul_f32 v[134:135], v[114:115], v[246:247]
	v_cvt_pk_bf16_f32 v128, v128, v129
	v_cvt_pk_bf16_f32 v129, v130, v131
	v_cvt_pk_bf16_f32 v130, v132, v133
	v_cvt_pk_bf16_f32 v131, v134, v135
	global_store_dwordx4 v249, v[128:131], s[2:3] offset:256
	v_mul_f32_e32 v132, v117, v117
	v_mul_f32_e32 v133, v119, v119
	v_mul_f32_e32 v134, v113, v113
	v_mul_f32_e32 v135, v115, v115
	v_fmac_f32_e32 v132, v116, v116
	v_fmac_f32_e32 v133, v118, v118
	v_fmac_f32_e32 v134, v112, v112
	v_fmac_f32_e32 v135, v114, v114
	v_add_f32_e32 v132, v132, v133
	v_add_f32_e32 v134, v134, v135
	v_add_f32_e32 v132, v132, v134
	v_add_f32_e32 v212, v212, v132
	s_add_u32 s8, s34, 0xa0000
	s_addc_u32 s9, s35, 0
	global_load_dwordx4 v[128:131], v248, s[8:9] offset:512
	global_load_dwordx4 v[132:135], v248, s[8:9] offset:528
	s_add_u32 s42, s38, 0x10000
	s_addc_u32 s43, s39, 0
	s_add_u32 s2, s26, 0x8000
	s_addc_u32 s3, s27, 0
	s_waitcnt vmcnt(13)
	v_pk_mul_f32 v[136:137], v[136:137], v[196:197]
	v_pk_mul_f32 v[138:139], v[138:139], v[198:199]
	v_pk_mul_f32 v[140:141], v[140:141], v[200:201]
	v_pk_mul_f32 v[142:143], v[142:143], v[202:203]
	v_mul_f32_e32 v136, v136, v205
	v_mul_f32_e32 v137, v137, v205
	v_mul_f32_e32 v138, v138, v205
	v_mul_f32_e32 v139, v139, v205
	v_mul_f32_e32 v140, v140, v205
	v_mul_f32_e32 v141, v141, v205
	v_mul_f32_e32 v142, v142, v205
	v_mul_f32_e32 v143, v143, v205
	v_pk_fma_f32 v[100:101], v[232:233], v[100:101], v[136:137]
	v_pk_fma_f32 v[102:103], v[234:235], v[102:103], v[138:139]
	v_pk_fma_f32 v[96:97], v[236:237], v[96:97], v[140:141]
	v_pk_fma_f32 v[98:99], v[238:239], v[98:99], v[142:143]
	global_store_dwordx4 v248, v[100:103], s[42:43] offset:512
	global_store_dwordx4 v248, v[96:99], s[42:43] offset:528
	v_pk_mul_f32 v[136:137], v[100:101], v[240:241]
	v_pk_mul_f32 v[138:139], v[102:103], v[242:243]
	v_pk_mul_f32 v[140:141], v[96:97], v[244:245]
	v_pk_mul_f32 v[142:143], v[98:99], v[246:247]
	v_cvt_pk_bf16_f32 v136, v136, v137
	v_cvt_pk_bf16_f32 v137, v138, v139
	v_cvt_pk_bf16_f32 v138, v140, v141
	v_cvt_pk_bf16_f32 v139, v142, v143
	global_store_dwordx4 v249, v[136:139], s[2:3] offset:256
	v_mul_f32_e32 v140, v101, v101
	v_mul_f32_e32 v141, v103, v103
	v_mul_f32_e32 v142, v97, v97
	v_mul_f32_e32 v143, v99, v99
	v_fmac_f32_e32 v140, v100, v100
	v_fmac_f32_e32 v141, v102, v102
	v_fmac_f32_e32 v142, v96, v96
	v_fmac_f32_e32 v143, v98, v98
	v_add_f32_e32 v140, v140, v141
	v_add_f32_e32 v142, v142, v143
	v_add_f32_e32 v140, v140, v142
	v_add_f32_e32 v213, v213, v140
	s_add_u32 s8, s34, 0xb0000
	s_addc_u32 s9, s35, 0
	global_load_dwordx4 v[136:139], v248, s[8:9] offset:512
	global_load_dwordx4 v[140:143], v248, s[8:9] offset:528
	s_add_u32 s42, s38, 0x20000
	s_addc_u32 s43, s39, 0
	s_add_u32 s2, s26, 0x10000
	s_addc_u32 s3, s27, 0
	s_waitcnt vmcnt(16)
	v_pk_mul_f32 v[144:145], v[144:145], v[196:197]
	v_pk_mul_f32 v[146:147], v[146:147], v[198:199]
	v_pk_mul_f32 v[148:149], v[148:149], v[200:201]
	v_pk_mul_f32 v[150:151], v[150:151], v[202:203]
	v_mul_f32_e32 v144, v144, v206
	v_mul_f32_e32 v145, v145, v206
	v_mul_f32_e32 v146, v146, v206
	v_mul_f32_e32 v147, v147, v206
	v_mul_f32_e32 v148, v148, v206
	v_mul_f32_e32 v149, v149, v206
	v_mul_f32_e32 v150, v150, v206
	v_mul_f32_e32 v151, v151, v206
	v_pk_fma_f32 v[84:85], v[232:233], v[84:85], v[144:145]
	v_pk_fma_f32 v[86:87], v[234:235], v[86:87], v[146:147]
	v_pk_fma_f32 v[80:81], v[236:237], v[80:81], v[148:149]
	v_pk_fma_f32 v[82:83], v[238:239], v[82:83], v[150:151]
	global_store_dwordx4 v248, v[84:87], s[42:43] offset:512
	global_store_dwordx4 v248, v[80:83], s[42:43] offset:528
	v_pk_mul_f32 v[144:145], v[84:85], v[240:241]
	v_pk_mul_f32 v[146:147], v[86:87], v[242:243]
	v_pk_mul_f32 v[148:149], v[80:81], v[244:245]
	v_pk_mul_f32 v[150:151], v[82:83], v[246:247]
	v_cvt_pk_bf16_f32 v144, v144, v145
	v_cvt_pk_bf16_f32 v145, v146, v147
	v_cvt_pk_bf16_f32 v146, v148, v149
	v_cvt_pk_bf16_f32 v147, v150, v151
	global_store_dwordx4 v249, v[144:147], s[2:3] offset:256
	v_mul_f32_e32 v148, v85, v85
	v_mul_f32_e32 v149, v87, v87
	v_mul_f32_e32 v150, v81, v81
	v_mul_f32_e32 v151, v83, v83
	v_fmac_f32_e32 v148, v84, v84
	v_fmac_f32_e32 v149, v86, v86
	v_fmac_f32_e32 v150, v80, v80
	v_fmac_f32_e32 v151, v82, v82
	v_add_f32_e32 v148, v148, v149
	v_add_f32_e32 v150, v150, v151
	v_add_f32_e32 v148, v148, v150
	v_add_f32_e32 v214, v214, v148
	s_add_u32 s42, s38, 0x30000
	s_addc_u32 s43, s39, 0
	s_add_u32 s2, s26, 0x18000
	s_addc_u32 s3, s27, 0
	s_waitcnt vmcnt(17)
; __device__ __forceinline__ unsigned cvt_pk_bf16(float lo, float hi) { unsigned r; asm volatile("v_cvt_pk_bf16_f32 %0, %1, %2" : "=v"(r) : "v"(lo), "v"(hi)); return r; }
;     static __device__ __forceinline__ void run(const f32x4 (&acc)[2][2][4][2], const Unit& u, int wr, int wc, int fr, int fq, const float* xin, float* xout, const float* gate, float gs, const float* lazy_ssq, const float* lazy_g, ...
;     ...
;                 for (int j = 0; j < 2; ++j) { const int i_ = 2 * pp + j, ai = i_ >> 2, m = i_ & 3; const unsigned off = (row0 + ai * HALF + m * 16) * 1024u + col;
;                     const f32x4 xi0 = xq[pp & 1][j][0], xi1 = xq[pp & 1][j][1];
;                     f32x4 xo0 = gv[0] * acc[ai][bj][m][0], xo1 = gv[1] * acc[ai][bj][m][1];
;                     if (LAZY) { xo0 = xo0 + xi0 * lg[0] * rl[ai][m]; xo1 = xo1 + xi1 * lg[1] * rl[ai][m]; } else { xo0 = xo0 + xi0; xo1 = xo1 + xi1; }
;                     *(f32x4*)(xout + off) = xo0; *(f32x4*)(xout + off + 4) = xo1;
;                     if (aout) { const f32x4 a0 = xo0 * wv[0], a1 = xo1 * wv[1]; u32x4 w; w.x = cvt_pk_bf16(a0[0], a0[1]); w.y = cvt_pk_bf16(a0[2], a0[3]); w.z = cvt_pk_bf16(a1[0], a1[1]); w.w = cvt_pk_bf16(a1[2], a1[3]);
;                         *(u32x4*)(aout + off) = w;
;                         sq[ai][m] += ((xo0[0] * xo0[0] + xo0[1] * xo0[1]) + (xo0[2] * xo0[2] + xo0[3] * xo0[3])) + ((xo1[0] * xo1[0] + xo1[1] * xo1[1]) + (xo1[2] * xo1[2] + xo1[3] * xo1[3]));
	v_pk_mul_f32 v[152:153], v[152:153], v[196:197]
	v_pk_mul_f32 v[154:155], v[154:155], v[198:199]
	v_pk_mul_f32 v[156:157], v[156:157], v[200:201]
	v_pk_mul_f32 v[158:159], v[158:159], v[202:203]
	v_mul_f32_e32 v152, v152, v207
	v_mul_f32_e32 v153, v153, v207
	v_mul_f32_e32 v154, v154, v207
	v_mul_f32_e32 v155, v155, v207
	v_mul_f32_e32 v156, v156, v207
	v_mul_f32_e32 v157, v157, v207
	v_mul_f32_e32 v158, v158, v207
	v_mul_f32_e32 v159, v159, v207
	v_pk_fma_f32 v[68:69], v[232:233], v[68:69], v[152:153]
	v_pk_fma_f32 v[70:71], v[234:235], v[70:71], v[154:155]
	v_pk_fma_f32 v[64:65], v[236:237], v[64:65], v[156:157]
	v_pk_fma_f32 v[66:67], v[238:239], v[66:67], v[158:159]
	global_store_dwordx4 v248, v[68:71], s[42:43] offset:512
	global_store_dwordx4 v248, v[64:67], s[42:43] offset:528
	v_pk_mul_f32 v[152:153], v[68:69], v[240:241]
	v_pk_mul_f32 v[154:155], v[70:71], v[242:243]
	v_pk_mul_f32 v[156:157], v[64:65], v[244:245]
	v_pk_mul_f32 v[158:159], v[66:67], v[246:247]
	v_cvt_pk_bf16_f32 v152, v152, v153
	v_cvt_pk_bf16_f32 v153, v154, v155
	v_cvt_pk_bf16_f32 v154, v156, v157
	v_cvt_pk_bf16_f32 v155, v158, v159
	global_store_dwordx4 v249, v[152:155], s[2:3] offset:256
	v_mul_f32_e32 v156, v69, v69
	v_mul_f32_e32 v157, v71, v71
	v_mul_f32_e32 v158, v65, v65
	v_mul_f32_e32 v159, v67, v67
	v_fmac_f32_e32 v156, v68, v68
	v_fmac_f32_e32 v157, v70, v70
	v_fmac_f32_e32 v158, v64, v64
	v_fmac_f32_e32 v159, v66, v66
	v_add_f32_e32 v156, v156, v157
	v_add_f32_e32 v158, v158, v159
	v_add_f32_e32 v156, v156, v158
	v_add_f32_e32 v215, v215, v156
	s_add_u32 s42, s38, 0x80000
	s_addc_u32 s43, s39, 0
	s_add_u32 s2, s26, 0x40000
	s_addc_u32 s3, s27, 0
	s_waitcnt vmcnt(18)
	v_pk_mul_f32 v[180:181], v[180:181], v[196:197]
	v_pk_mul_f32 v[182:183], v[182:183], v[198:199]
	v_pk_mul_f32 v[184:185], v[184:185], v[200:201]
	v_pk_mul_f32 v[186:187], v[186:187], v[202:203]
	v_mul_f32_e32 v180, v180, v208
	v_mul_f32_e32 v181, v181, v208
	v_mul_f32_e32 v182, v182, v208
	v_mul_f32_e32 v183, v183, v208
	v_mul_f32_e32 v184, v184, v208
	v_mul_f32_e32 v185, v185, v208
	v_mul_f32_e32 v186, v186, v208
	v_mul_f32_e32 v187, v187, v208
	v_pk_fma_f32 v[52:53], v[232:233], v[52:53], v[180:181]
	v_pk_fma_f32 v[54:55], v[234:235], v[54:55], v[182:183]
	v_pk_fma_f32 v[48:49], v[236:237], v[48:49], v[184:185]
	v_pk_fma_f32 v[50:51], v[238:239], v[50:51], v[186:187]
	global_store_dwordx4 v248, v[52:55], s[42:43] offset:512
	global_store_dwordx4 v248, v[48:51], s[42:43] offset:528
	v_pk_mul_f32 v[180:181], v[52:53], v[240:241]
	v_pk_mul_f32 v[182:183], v[54:55], v[242:243]
	v_pk_mul_f32 v[184:185], v[48:49], v[244:245]
	v_pk_mul_f32 v[186:187], v[50:51], v[246:247]
	v_cvt_pk_bf16_f32 v180, v180, v181
	v_cvt_pk_bf16_f32 v181, v182, v183
	v_cvt_pk_bf16_f32 v182, v184, v185
	v_cvt_pk_bf16_f32 v183, v186, v187
	global_store_dwordx4 v249, v[180:183], s[2:3] offset:256
	v_mul_f32_e32 v184, v53, v53
	v_mul_f32_e32 v185, v55, v55
	v_mul_f32_e32 v186, v49, v49
	v_mul_f32_e32 v187, v51, v51
	v_fmac_f32_e32 v184, v52, v52
	v_fmac_f32_e32 v185, v54, v54
	v_fmac_f32_e32 v186, v48, v48
	v_fmac_f32_e32 v187, v50, v50
	v_add_f32_e32 v184, v184, v185
	v_add_f32_e32 v186, v186, v187
	v_add_f32_e32 v184, v184, v186
	v_add_f32_e32 v172, v172, v184
	s_add_u32 s42, s38, 0x90000
	s_addc_u32 s43, s39, 0
	s_add_u32 s2, s26, 0x48000
	s_addc_u32 s3, s27, 0
	s_waitcnt vmcnt(19)
	v_pk_mul_f32 v[188:189], v[188:189], v[196:197]
	v_pk_mul_f32 v[190:191], v[190:191], v[198:199]
	v_pk_mul_f32 v[192:193], v[192:193], v[200:201]
	v_pk_mul_f32 v[194:195], v[194:195], v[202:203]
	v_mul_f32_e32 v188, v188, v209
	v_mul_f32_e32 v189, v189, v209
	v_mul_f32_e32 v190, v190, v209
	v_mul_f32_e32 v191, v191, v209
	v_mul_f32_e32 v192, v192, v209
	v_mul_f32_e32 v193, v193, v209
	v_mul_f32_e32 v194, v194, v209
	v_mul_f32_e32 v195, v195, v209
	v_pk_fma_f32 v[36:37], v[232:233], v[36:37], v[188:189]
	v_pk_fma_f32 v[38:39], v[234:235], v[38:39], v[190:191]
	v_pk_fma_f32 v[32:33], v[236:237], v[32:33], v[192:193]
	v_pk_fma_f32 v[34:35], v[238:239], v[34:35], v[194:195]
	global_store_dwordx4 v248, v[36:39], s[42:43] offset:512
	global_store_dwordx4 v248, v[32:35], s[42:43] offset:528
	v_pk_mul_f32 v[188:189], v[36:37], v[240:241]
	v_pk_mul_f32 v[190:191], v[38:39], v[242:243]
	v_pk_mul_f32 v[192:193], v[32:33], v[244:245]
	v_pk_mul_f32 v[194:195], v[34:35], v[246:247]
	v_cvt_pk_bf16_f32 v188, v188, v189
	v_cvt_pk_bf16_f32 v189, v190, v191
	v_cvt_pk_bf16_f32 v190, v192, v193
	v_cvt_pk_bf16_f32 v191, v194, v195
	global_store_dwordx4 v249, v[188:191], s[2:3] offset:256
	v_mul_f32_e32 v192, v37, v37
	v_mul_f32_e32 v193, v39, v39
	v_mul_f32_e32 v194, v33, v33
	v_mul_f32_e32 v195, v35, v35
	v_fmac_f32_e32 v192, v36, v36
	v_fmac_f32_e32 v193, v38, v38
	v_fmac_f32_e32 v194, v32, v32
	v_fmac_f32_e32 v195, v34, v34
	v_add_f32_e32 v192, v192, v193
	v_add_f32_e32 v194, v194, v195
	v_add_f32_e32 v192, v192, v194
	v_add_f32_e32 v173, v173, v192
	s_add_u32 s42, s38, 0xa0000
	s_addc_u32 s43, s39, 0
	s_add_u32 s2, s26, 0x50000
	s_addc_u32 s3, s27, 0
	s_waitcnt vmcnt(17)
; __device__ __forceinline__ unsigned cvt_pk_bf16(float lo, float hi) { unsigned r; asm volatile("v_cvt_pk_bf16_f32 %0, %1, %2" : "=v"(r) : "v"(lo), "v"(hi)); return r; }
;     static __device__ __forceinline__ void run(const f32x4 (&acc)[2][2][4][2], const Unit& u, int wr, int wc, int fr, int fq, const float* xin, float* xout, const float* gate, float gs, const float* lazy_ssq, const float* lazy_g, ...
;     ...
;                 for (int j = 0; j < 2; ++j) { const int i_ = 2 * pp + j, ai = i_ >> 2, m = i_ & 3; const unsigned off = (row0 + ai * HALF + m * 16) * 1024u + col;
;                     const f32x4 xi0 = xq[pp & 1][j][0], xi1 = xq[pp & 1][j][1];
;                     f32x4 xo0 = gv[0] * acc[ai][bj][m][0], xo1 = gv[1] * acc[ai][bj][m][1];
;                     if (LAZY) { xo0 = xo0 + xi0 * lg[0] * rl[ai][m]; xo1 = xo1 + xi1 * lg[1] * rl[ai][m]; } else { xo0 = xo0 + xi0; xo1 = xo1 + xi1; }
;                     *(f32x4*)(xout + off) = xo0; *(f32x4*)(xout + off + 4) = xo1;
;                     if (aout) { const f32x4 a0 = xo0 * wv[0], a1 = xo1 * wv[1]; u32x4 w; w.x = cvt_pk_bf16(a0[0], a0[1]); w.y = cvt_pk_bf16(a0[2], a0[3]); w.z = cvt_pk_bf16(a1[0], a1[1]); w.w = cvt_pk_bf16(a1[2], a1[3]);
;                         *(u32x4*)(aout + off) = w;
;                         sq[ai][m] += ((xo0[0] * xo0[0] + xo0[1] * xo0[1]) + (xo0[2] * xo0[2] + xo0[3] * xo0[3])) + ((xo1[0] * xo1[0] + xo1[1] * xo1[1]) + (xo1[2] * xo1[2] + xo1[3] * xo1[3]));
;                         if (WG2) { const f32x4 b0 = xo0 * w2[0], b1 = xo1 * w2[1]; sqb[ai][m] += ((b0[0] * b0[0] + b0[1] * b0[1]) + (b0[2] * b0[2] + b0[3] * b0[3])) + ((b1[0] * b1[0] + b1[1] * b1[1]) + (b1[2] * b1[2] + b1[3] * b1[3])); } } }
;                 asm volatile("" ::: "memory");
;             }
;     ...
;         }
;         if (aout) {
; #pragma unroll
;             for (int ai = 0; ai < 2; ++ai)
; #pragma unroll
;                 for (int m = 0; m < 4; ++m) { float s = sq[ai][m]; s = xadd<16>(s); s = xadd<32>(s);
;                     float sb = sqb[ai][m]; if (WG2) { sb = xadd<16>(sb); sb = xadd<32>(sb); }
;                     if (fq == 0) { unsafeAtomicAdd(ssq_out + (row0 + ai * HALF + m * 16), s); if (WG2) unsafeAtomicAdd(ssqB_out + (row0 + ai * HALF + m * 16), sb); } }
	v_pk_mul_f32 v[128:129], v[128:129], v[196:197]
	v_pk_mul_f32 v[130:131], v[130:131], v[198:199]
	v_pk_mul_f32 v[132:133], v[132:133], v[200:201]
	v_pk_mul_f32 v[134:135], v[134:135], v[202:203]
	v_mul_f32_e32 v128, v128, v210
	v_mul_f32_e32 v129, v129, v210
	v_mul_f32_e32 v130, v130, v210
	v_mul_f32_e32 v131, v131, v210
	v_mul_f32_e32 v132, v132, v210
	v_mul_f32_e32 v133, v133, v210
	v_mul_f32_e32 v134, v134, v210
	v_mul_f32_e32 v135, v135, v210
	v_pk_fma_f32 v[20:21], v[232:233], v[20:21], v[128:129]
	v_pk_fma_f32 v[22:23], v[234:235], v[22:23], v[130:131]
	v_pk_fma_f32 v[16:17], v[236:237], v[16:17], v[132:133]
	v_pk_fma_f32 v[18:19], v[238:239], v[18:19], v[134:135]
	global_store_dwordx4 v248, v[20:23], s[42:43] offset:512
	global_store_dwordx4 v248, v[16:19], s[42:43] offset:528
	v_pk_mul_f32 v[128:129], v[20:21], v[240:241]
	v_pk_mul_f32 v[130:131], v[22:23], v[242:243]
	v_pk_mul_f32 v[132:133], v[16:17], v[244:245]
	v_pk_mul_f32 v[134:135], v[18:19], v[246:247]
	v_cvt_pk_bf16_f32 v128, v128, v129
	v_cvt_pk_bf16_f32 v129, v130, v131
	v_cvt_pk_bf16_f32 v130, v132, v133
	v_cvt_pk_bf16_f32 v131, v134, v135
	global_store_dwordx4 v249, v[128:131], s[2:3] offset:256
	v_mul_f32_e32 v132, v21, v21
	v_mul_f32_e32 v133, v23, v23
	v_mul_f32_e32 v134, v17, v17
	v_mul_f32_e32 v135, v19, v19
	v_fmac_f32_e32 v132, v20, v20
	v_fmac_f32_e32 v133, v22, v22
	v_fmac_f32_e32 v134, v16, v16
	v_fmac_f32_e32 v135, v18, v18
	v_add_f32_e32 v132, v132, v133
	v_add_f32_e32 v134, v134, v135
	v_add_f32_e32 v132, v132, v134
	v_add_f32_e32 v174, v174, v132
	s_add_u32 s42, s38, 0xb0000
	s_addc_u32 s43, s39, 0
	s_add_u32 s2, s26, 0x58000
	s_addc_u32 s3, s27, 0
	s_waitcnt vmcnt(15)
	v_pk_mul_f32 v[136:137], v[136:137], v[196:197]
	v_pk_mul_f32 v[138:139], v[138:139], v[198:199]
	v_pk_mul_f32 v[140:141], v[140:141], v[200:201]
	v_pk_mul_f32 v[142:143], v[142:143], v[202:203]
	v_mul_f32_e32 v136, v136, v211
	v_mul_f32_e32 v137, v137, v211
	v_mul_f32_e32 v138, v138, v211
	v_mul_f32_e32 v139, v139, v211
	v_mul_f32_e32 v140, v140, v211
	v_mul_f32_e32 v141, v141, v211
	v_mul_f32_e32 v142, v142, v211
	v_mul_f32_e32 v143, v143, v211
	v_pk_fma_f32 v[4:5], v[232:233], v[4:5], v[136:137]
	v_pk_fma_f32 v[6:7], v[234:235], v[6:7], v[138:139]
	v_pk_fma_f32 v[0:1], v[236:237], v[0:1], v[140:141]
	v_pk_fma_f32 v[2:3], v[238:239], v[2:3], v[142:143]
	global_store_dwordx4 v248, v[4:7], s[42:43] offset:512
	global_store_dwordx4 v248, v[0:3], s[42:43] offset:528
	v_pk_mul_f32 v[136:137], v[4:5], v[240:241]
	v_pk_mul_f32 v[138:139], v[6:7], v[242:243]
	v_pk_mul_f32 v[140:141], v[0:1], v[244:245]
	v_pk_mul_f32 v[142:143], v[2:3], v[246:247]
	v_cvt_pk_bf16_f32 v136, v136, v137
	v_cvt_pk_bf16_f32 v137, v138, v139
	v_cvt_pk_bf16_f32 v138, v140, v141
	v_cvt_pk_bf16_f32 v139, v142, v143
	global_store_dwordx4 v249, v[136:139], s[2:3] offset:256
	v_mul_f32_e32 v140, v5, v5
	v_mul_f32_e32 v141, v7, v7
	v_mul_f32_e32 v142, v1, v1
	v_mul_f32_e32 v143, v3, v3
	v_fmac_f32_e32 v140, v4, v4
	v_fmac_f32_e32 v141, v6, v6
	v_fmac_f32_e32 v142, v0, v0
	v_fmac_f32_e32 v143, v2, v2
	v_add_f32_e32 v140, v140, v141
	v_add_f32_e32 v142, v142, v143
	v_add_f32_e32 v140, v140, v142
	v_add_f32_e32 v175, v175, v140
	ds_swizzle_b32 v128, v212 offset:swizzle(SWAP,16)
	ds_swizzle_b32 v129, v213 offset:swizzle(SWAP,16)
	ds_swizzle_b32 v130, v214 offset:swizzle(SWAP,16)
	ds_swizzle_b32 v131, v215 offset:swizzle(SWAP,16)
	ds_swizzle_b32 v132, v172 offset:swizzle(SWAP,16)
	ds_swizzle_b32 v133, v173 offset:swizzle(SWAP,16)
	ds_swizzle_b32 v134, v174 offset:swizzle(SWAP,16)
	ds_swizzle_b32 v135, v175 offset:swizzle(SWAP,16)
	s_waitcnt lgkmcnt(0)
	v_add_f32_e32 v212, v212, v128
	v_add_f32_e32 v213, v213, v129
	v_add_f32_e32 v214, v214, v130
	v_add_f32_e32 v215, v215, v131
	v_add_f32_e32 v172, v172, v132
	v_add_f32_e32 v173, v173, v133
	v_add_f32_e32 v174, v174, v134
	v_add_f32_e32 v175, v175, v135
	v_mov_b32_e32 v128, v212
	v_mov_b32_e32 v129, v213
	v_mov_b32_e32 v130, v214
	v_mov_b32_e32 v131, v215
	v_mov_b32_e32 v132, v172
	v_mov_b32_e32 v133, v173
	v_mov_b32_e32 v134, v174
	v_mov_b32_e32 v135, v175
	s_nop 1
	v_permlane32_swap_b32_e32 v212, v128
	v_permlane32_swap_b32_e32 v213, v129
	v_permlane32_swap_b32_e32 v214, v130
	v_permlane32_swap_b32_e32 v215, v131
	v_permlane32_swap_b32_e32 v172, v132
	v_permlane32_swap_b32_e32 v173, v133
	v_permlane32_swap_b32_e32 v174, v134
	v_permlane32_swap_b32_e32 v175, v135
	v_mov_b32_e32 v144, 0x20880
	ds_read_b128 v[144:147], v144
	s_lshl_b32 s8, s63, 8
	s_lshl_b32 s9, s65, 6
	s_add_i32 s8, s8, s9
	v_or_b32_e32 v176, s8, v230
	v_lshlrev_b32_e32 v176, 2, v176
	s_waitcnt lgkmcnt(0)
	v_readfirstlane_b32 s10, v144
	v_readfirstlane_b32 s11, v145
	v_readfirstlane_b32 s28, v146
	v_readfirstlane_b32 s29, v147
	s_mov_b64 s[8:9], exec
	s_mov_b64 exec, 0xffff
	v_add_f32_e32 v212, v212, v128
	v_add_f32_e32 v213, v213, v129
	v_add_f32_e32 v214, v214, v130
	v_add_f32_e32 v215, v215, v131
	v_add_f32_e32 v172, v172, v132
	v_add_f32_e32 v173, v173, v133
	v_add_f32_e32 v174, v174, v134
	v_add_f32_e32 v175, v175, v135
	s_nop 3
	global_atomic_add_f32 v176, v212, s[10:11]
	global_atomic_add_f32 v176, v213, s[10:11] offset:64
	global_atomic_add_f32 v176, v214, s[10:11] offset:128
	global_atomic_add_f32 v176, v215, s[10:11] offset:192
	global_atomic_add_f32 v176, v172, s[10:11] offset:512
	global_atomic_add_f32 v176, v173, s[10:11] offset:576
	global_atomic_add_f32 v176, v174, s[10:11] offset:640
	global_atomic_add_f32 v176, v175, s[10:11] offset:704
	s_mov_b64 exec, s[8:9]
	s_mov_b64 s[2:3], 0
	s_mov_b64 s[26:27], 0

;     static __device__ __forceinline__ void run(const f32x4 (&acc)[2][2][4][2], const Unit& u, int wr, int wc, int fr, int fq, const float* xin, float* xout, const float* gate, float gs, const float* lazy_ssq, const float* lazy_g, ...
;         const unsigned b = (unsigned)(u.pm * BM) >> 13; const unsigned row0 = u.pm * BM + wr * 64 + fr; const unsigned col0 = u.pn * BM + wc * 32 + 8 * fq;
;         float rl[2][4], sq[2][4], sqb[2][4];
; #pragma unroll
;         for (int ai = 0; ai < 2; ++ai)
; #pragma unroll
;             for (int m = 0; m < 4; ++m) { rl[ai][m] = LAZY ? __builtin_amdgcn_rsqf(lazy_ssq[row0 + ai * HALF + m * 16] * (1.0f / 1024.0f) + 1e-6f) : 1.0f; sq[ai][m] = 0.f; sqb[ai][m] = 0.f; }
; #pragma unroll
;         for (int bj = 0; bj < 2; ++bj) {
;             const unsigned col = col0 + bj * HALF;
;             f32x4 gv[2], lg[2], wv[2], w2[2];
; #pragma unroll
;             for (int n = 0; n < 2; ++n) {
;                 gv[n] = *(const f32x4*)(gate + (b * 9216u + col + 4 * n)) * gs;
;                 lg[n] = (f32x4){1.f, 1.f, 1.f, 1.f}; if (LAZY) lg[n] = *(const f32x4*)(lazy_g + col + 4 * n);
;                 wv[n] = (f32x4){0.f, 0.f, 0.f, 0.f}; w2[n] = (f32x4){1.f, 1.f, 1.f, 1.f};
;                 if (aout) { wv[n] = *(const f32x4*)(wg + col + 4 * n) * (*(const f32x4*)(wsc + (b * 9216u + col + 4 * n)) + 1.0f); if (WG2) { w2[n] = *(const f32x4*)(wg2 + col + 4 * n); wv[n] = wv[n] * w2[n]; } }
;             }
;             f32x4 xq[2][2][2];
;     ...
;             constexpr bool DEEP = !LAZY && !WG2;
;             if (DEEP) RES_LD(0, 0);
; #pragma unroll
;             for (int pp = 0; pp < 4; ++pp) {
;                 if (DEEP) { if (pp < 3) RES_LD((pp + 1) & 1, pp + 1); } else RES_LD(pp & 1, pp);
; #pragma unroll
;                 for (int j = 0; j < 2; ++j) { const int i_ = 2 * pp + j, ai = i_ >> 2, m = i_ & 3; const unsigned off = (row0 + ai * HALF + m * 16) * 1024u + col;
;                     const f32x4 xi0 = xq[pp & 1][j][0], xi1 = xq[pp & 1][j][1];
;                     f32x4 xo0 = gv[0] * acc[ai][bj][m][0], xo1 = gv[1] * acc[ai][bj][m][1];
;                     if (LAZY) { xo0 = xo0 + xi0 * lg[0] * rl[ai][m]; xo1 = xo1 + xi1 * lg[1] * rl[ai][m]; } else { xo0 = xo0 + xi0; xo1 = xo1 + xi1; }
;                     *(f32x4*)(xout + off) = xo0; *(f32x4*)(xout + off + 4) = xo1;
.LBB0_375:
	s_and_b64 vcc, exec, s[8:9]
	s_cbranch_vccz .LBB0_443
	v_mov_b32_e32 v128, 0x20810
	ds_read_b128 v[128:131], v128
	v_mov_b32_e32 v132, 0x20820
	ds_read_b128 v[132:135], v132
	v_mov_b32_e32 v136, 0x20830
	ds_read_b128 v[136:139], v136
	v_mov_b32_e32 v140, 0x20860
	ds_read_b128 v[140:143], v140
	v_mov_b32_e32 v144, 0x20870
	ds_read_b128 v[144:147], v144
	v_mov_b32_e32 v148, 0x20850
	ds_read_b128 v[148:151], v148
	v_mov_b32_e32 v152, 0x20808
	ds_read_b32 v152, v152
	s_waitcnt lgkmcnt(0)
	v_readfirstlane_b32 s38, v128
	v_readfirstlane_b32 s39, v129
	v_readfirstlane_b32 s34, v134
	v_readfirstlane_b32 s35, v135
	v_readfirstlane_b32 s40, v136
	v_readfirstlane_b32 s41, v137
	v_readfirstlane_b32 s26, v140
	v_readfirstlane_b32 s27, v141
	v_readfirstlane_b32 s28, v142
	v_readfirstlane_b32 s29, v143
	v_readfirstlane_b32 s30, v144
	v_readfirstlane_b32 s31, v145
	v_readfirstlane_b32 s36, v152
	v_readfirstlane_b32 s10, v146
	v_readfirstlane_b32 s11, v147
	v_mov_b32_e32 v212, 0
	v_mov_b32_e32 v213, 0
	v_mov_b32_e32 v214, 0
	v_mov_b32_e32 v215, 0
	v_mov_b32_e32 v172, 0
	v_mov_b32_e32 v173, 0
	v_mov_b32_e32 v174, 0
	v_mov_b32_e32 v175, 0
	v_mov_b32_e32 v204, 0
	v_mov_b32_e32 v205, 0
	v_mov_b32_e32 v206, 0
	v_mov_b32_e32 v207, 0
	v_mov_b32_e32 v208, 0
	v_mov_b32_e32 v209, 0
	v_mov_b32_e32 v210, 0
	v_mov_b32_e32 v211, 0
	s_lshl_b32 s8, s63, 8
	s_lshl_b32 s9, s65, 6
	s_add_i32 s8, s8, s9
	v_or_b32_e32 v231, s8, v230
	s_lshl_b32 s9, s62, 8
	s_lshl_b32 s8, s64, 5
	s_or_b32 s9, s9, s8
	v_lshl_or_b32 v176, v229, 3, s9
	v_lshl_add_u32 v248, v231, 10, v176
	v_lshlrev_b32_e32 v249, 1, v248
	v_lshlrev_b32_e32 v248, 2, v248
	s_bfe_u32 s37, s63, 0x130005
	s_mulk_i32 s37, 0x2400
	v_add_u32_e32 v231, s37, v176
	v_lshlrev_b32_e32 v231, 2, v231
	v_lshlrev_b32_e32 v176, 2, v176
	global_load_dwordx4 v[232:235], v231, s[40:41] offset:0
	global_load_dwordx4 v[236:239], v231, s[40:41] offset:16
	global_load_dwordx4 v[240:243], v176, s[28:29] offset:0
	global_load_dwordx4 v[244:247], v176, s[28:29] offset:16
	global_load_dwordx4 v[188:191], v231, s[30:31] offset:0
	global_load_dwordx4 v[192:195], v231, s[30:31] offset:16
	global_load_dwordx4 v[196:199], v176, s[10:11] offset:0
	global_load_dwordx4 v[200:203], v176, s[10:11] offset:16
	s_mov_b64 s[8:9], s[34:35]
	global_load_dwordx4 v[128:131], v248, s[8:9] offset:0
	global_load_dwordx4 v[132:135], v248, s[8:9] offset:16
	s_add_u32 s8, s34, 0x10000
	s_addc_u32 s9, s35, 0
	global_load_dwordx4 v[136:139], v248, s[8:9] offset:0
	global_load_dwordx4 v[140:143], v248, s[8:9] offset:16
	s_add_u32 s8, s34, 0x20000
	s_addc_u32 s9, s35, 0
	global_load_dwordx4 v[144:147], v248, s[8:9] offset:0
	global_load_dwordx4 v[148:151], v248, s[8:9] offset:16
	s_add_u32 s8, s34, 0x30000
	s_addc_u32 s9, s35, 0
	global_load_dwordx4 v[152:155], v248, s[8:9] offset:0
	global_load_dwordx4 v[156:159], v248, s[8:9] offset:16
	s_add_u32 s8, s34, 0x80000
	s_addc_u32 s9, s35, 0
	global_load_dwordx4 v[180:183], v248, s[8:9] offset:0
	global_load_dwordx4 v[184:187], v248, s[8:9] offset:16
	s_waitcnt vmcnt(10)
	v_pk_mul_f32 v[232:233], s[36:37], v[232:233] op_sel_hi:[0,1]
	v_pk_mul_f32 v[234:235], s[36:37], v[234:235] op_sel_hi:[0,1]
	v_pk_mul_f32 v[236:237], s[36:37], v[236:237] op_sel_hi:[0,1]
	v_pk_mul_f32 v[238:239], s[36:37], v[238:239] op_sel_hi:[0,1]
	v_pk_add_f32 v[188:189], v[188:189], 1.0 op_sel_hi:[1,0]
	v_pk_add_f32 v[190:191], v[190:191], 1.0 op_sel_hi:[1,0]
	v_pk_add_f32 v[192:193], v[192:193], 1.0 op_sel_hi:[1,0]
	v_pk_add_f32 v[194:195], v[194:195], 1.0 op_sel_hi:[1,0]
	v_pk_mul_f32 v[240:241], v[240:241], v[188:189]
	v_pk_mul_f32 v[242:243], v[242:243], v[190:191]
	v_pk_mul_f32 v[244:245], v[244:245], v[192:193]
	v_pk_mul_f32 v[246:247], v[246:247], v[194:195]
	v_pk_mul_f32 v[240:241], v[240:241], v[196:197]
	v_pk_mul_f32 v[242:243], v[242:243], v[198:199]
	v_pk_mul_f32 v[244:245], v[244:245], v[200:201]
	v_pk_mul_f32 v[246:247], v[246:247], v[202:203]
	s_add_u32 s8, s34, 0x90000
	s_addc_u32 s9, s35, 0
	global_load_dwordx4 v[188:191], v248, s[8:9] offset:0
	global_load_dwordx4 v[192:195], v248, s[8:9] offset:16
	s_mov_b64 s[42:43], s[38:39]
	s_mov_b64 s[2:3], s[26:27]
	s_waitcnt vmcnt(10)
	v_pk_fma_f32 v[124:125], v[232:233], v[124:125], v[128:129]
	v_pk_fma_f32 v[126:127], v[234:235], v[126:127], v[130:131]
	v_pk_fma_f32 v[120:121], v[236:237], v[120:121], v[132:133]
	v_pk_fma_f32 v[122:123], v[238:239], v[122:123], v[134:135]
	global_store_dwordx4 v248, v[124:127], s[42:43] offset:0
	global_store_dwordx4 v248, v[120:123], s[42:43] offset:16
	v_pk_mul_f32 v[128:129], v[124:125], v[240:241]
	v_pk_mul_f32 v[130:131], v[126:127], v[242:243]
	v_pk_mul_f32 v[132:133], v[120:121], v[244:245]
	v_pk_mul_f32 v[134:135], v[122:123], v[246:247]
	v_cvt_pk_bf16_f32 v128, v128, v129
	v_cvt_pk_bf16_f32 v129, v130, v131
	v_cvt_pk_bf16_f32 v130, v132, v133
	v_cvt_pk_bf16_f32 v131, v134, v135
	global_store_dwordx4 v249, v[128:131], s[2:3] offset:0
	v_mul_f32_e32 v132, v125, v125
	v_mul_f32_e32 v133, v127, v127
	v_mul_f32_e32 v134, v121, v121
	v_mul_f32_e32 v135, v123, v123
	v_fmac_f32_e32 v132, v124, v124
	v_fmac_f32_e32 v133, v126, v126
	v_fmac_f32_e32 v134, v120, v120
	v_fmac_f32_e32 v135, v122, v122
	v_add_f32_e32 v132, v132, v133
	v_add_f32_e32 v134, v134, v135
	v_add_f32_e32 v132, v132, v134
	v_add_f32_e32 v212, v212, v132
	v_pk_mul_f32 v[132:133], v[124:125], v[196:197]
	v_pk_mul_f32 v[134:135], v[126:127], v[198:199]
	v_pk_mul_f32 v[128:129], v[120:121], v[200:201]
	v_pk_mul_f32 v[130:131], v[122:123], v[202:203]
	v_mul_f32_e32 v133, v133, v133
	v_mul_f32_e32 v135, v135, v135
	v_fmac_f32_e32 v133, v132, v132
	v_fmac_f32_e32 v135, v134, v134
	v_add_f32_e32 v133, v133, v135
	v_mul_f32_e32 v129, v129, v129
	v_mul_f32_e32 v131, v131, v131
	v_fmac_f32_e32 v129, v128, v128
	v_fmac_f32_e32 v131, v130, v130
	v_add_f32_e32 v129, v129, v131
	v_add_f32_e32 v133, v133, v129
	v_add_f32_e32 v204, v204, v133
	s_add_u32 s8, s34, 0xa0000
	s_addc_u32 s9, s35, 0
	global_load_dwordx4 v[128:131], v248, s[8:9] offset:0
	global_load_dwordx4 v[132:135], v248, s[8:9] offset:16
	s_add_u32 s42, s38, 0x10000
	s_addc_u32 s43, s39, 0
	s_add_u32 s2, s26, 0x8000
	s_addc_u32 s3, s27, 0
	s_waitcnt vmcnt(13)
; __device__ __forceinline__ unsigned cvt_pk_bf16(float lo, float hi) { unsigned r; asm volatile("v_cvt_pk_bf16_f32 %0, %1, %2" : "=v"(r) : "v"(lo), "v"(hi)); return r; }
; #define RES_LD(buf, pp) do { _Pragma("unroll") for (int j = 0; j < 2; ++j) { const int i_ = 2 * (pp) + j; const unsigned off_ = (row0 + (i_ >> 2) * HALF + (i_ & 3) * 16) * 1024u + col; \
;                 xq[buf][j][0] = *(const f32x4*)(xin + off_); xq[buf][j][1] = *(const f32x4*)(xin + off_ + 4); } } while (0)
;     static __device__ __forceinline__ void run(const f32x4 (&acc)[2][2][4][2], const Unit& u, int wr, int wc, int fr, int fq, const float* xin, float* xout, const float* gate, float gs, const float* lazy_ssq, const float* lazy_g, ...
;     ...
;                 if (DEEP) { if (pp < 3) RES_LD((pp + 1) & 1, pp + 1); } else RES_LD(pp & 1, pp);
; #pragma unroll
;                 for (int j = 0; j < 2; ++j) { const int i_ = 2 * pp + j, ai = i_ >> 2, m = i_ & 3; const unsigned off = (row0 + ai * HALF + m * 16) * 1024u + col;
;                     const f32x4 xi0 = xq[pp & 1][j][0], xi1 = xq[pp & 1][j][1];
;                     f32x4 xo0 = gv[0] * acc[ai][bj][m][0], xo1 = gv[1] * acc[ai][bj][m][1];
;                     if (LAZY) { xo0 = xo0 + xi0 * lg[0] * rl[ai][m]; xo1 = xo1 + xi1 * lg[1] * rl[ai][m]; } else { xo0 = xo0 + xi0; xo1 = xo1 + xi1; }
;                     *(f32x4*)(xout + off) = xo0; *(f32x4*)(xout + off + 4) = xo1;
;                     if (aout) { const f32x4 a0 = xo0 * wv[0], a1 = xo1 * wv[1]; u32x4 w; w.x = cvt_pk_bf16(a0[0], a0[1]); w.y = cvt_pk_bf16(a0[2], a0[3]); w.z = cvt_pk_bf16(a1[0], a1[1]); w.w = cvt_pk_bf16(a1[2], a1[3]);
;                         *(u32x4*)(aout + off) = w;
;                         sq[ai][m] += ((xo0[0] * xo0[0] + xo0[1] * xo0[1]) + (xo0[2] * xo0[2] + xo0[3] * xo0[3])) + ((xo1[0] * xo1[0] + xo1[1] * xo1[1]) + (xo1[2] * xo1[2] + xo1[3] * xo1[3]));
;                         if (WG2) { const f32x4 b0 = xo0 * w2[0], b1 = xo1 * w2[1]; sqb[ai][m] += ((b0[0] * b0[0] + b0[1] * b0[1]) + (b0[2] * b0[2] + b0[3] * b0[3])) + ((b1[0] * b1[0] + b1[1] * b1[1]) + (b1[2] * b1[2] + b1[3] * b1[3])); } } }
	v_pk_fma_f32 v[108:109], v[232:233], v[108:109], v[136:137]
	v_pk_fma_f32 v[110:111], v[234:235], v[110:111], v[138:139]
	v_pk_fma_f32 v[104:105], v[236:237], v[104:105], v[140:141]
	v_pk_fma_f32 v[106:107], v[238:239], v[106:107], v[142:143]
	global_store_dwordx4 v248, v[108:111], s[42:43] offset:0
	global_store_dwordx4 v248, v[104:107], s[42:43] offset:16
	v_pk_mul_f32 v[136:137], v[108:109], v[240:241]
	v_pk_mul_f32 v[138:139], v[110:111], v[242:243]
	v_pk_mul_f32 v[140:141], v[104:105], v[244:245]
	v_pk_mul_f32 v[142:143], v[106:107], v[246:247]
	v_cvt_pk_bf16_f32 v136, v136, v137
	v_cvt_pk_bf16_f32 v137, v138, v139
	v_cvt_pk_bf16_f32 v138, v140, v141
	v_cvt_pk_bf16_f32 v139, v142, v143
	global_store_dwordx4 v249, v[136:139], s[2:3] offset:0
	v_mul_f32_e32 v140, v109, v109
	v_mul_f32_e32 v141, v111, v111
	v_mul_f32_e32 v142, v105, v105
	v_mul_f32_e32 v143, v107, v107
	v_fmac_f32_e32 v140, v108, v108
	v_fmac_f32_e32 v141, v110, v110
	v_fmac_f32_e32 v142, v104, v104
	v_fmac_f32_e32 v143, v106, v106
	v_add_f32_e32 v140, v140, v141
	v_add_f32_e32 v142, v142, v143
	v_add_f32_e32 v140, v140, v142
	v_add_f32_e32 v213, v213, v140
	v_pk_mul_f32 v[140:141], v[108:109], v[196:197]
	v_pk_mul_f32 v[142:143], v[110:111], v[198:199]
	v_pk_mul_f32 v[136:137], v[104:105], v[200:201]
	v_pk_mul_f32 v[138:139], v[106:107], v[202:203]
	v_mul_f32_e32 v141, v141, v141
	v_mul_f32_e32 v143, v143, v143
	v_fmac_f32_e32 v141, v140, v140
	v_fmac_f32_e32 v143, v142, v142
	v_add_f32_e32 v141, v141, v143
	v_mul_f32_e32 v137, v137, v137
	v_mul_f32_e32 v139, v139, v139
	v_fmac_f32_e32 v137, v136, v136
	v_fmac_f32_e32 v139, v138, v138
	v_add_f32_e32 v137, v137, v139
	v_add_f32_e32 v141, v141, v137
	v_add_f32_e32 v205, v205, v141
	s_add_u32 s8, s34, 0xb0000
	s_addc_u32 s9, s35, 0
	global_load_dwordx4 v[136:139], v248, s[8:9] offset:0
	global_load_dwordx4 v[140:143], v248, s[8:9] offset:16
	s_add_u32 s42, s38, 0x20000
	s_addc_u32 s43, s39, 0
	s_add_u32 s2, s26, 0x10000
	s_addc_u32 s3, s27, 0
	s_waitcnt vmcnt(16)
	v_pk_fma_f32 v[92:93], v[232:233], v[92:93], v[144:145]
	v_pk_fma_f32 v[94:95], v[234:235], v[94:95], v[146:147]
	v_pk_fma_f32 v[88:89], v[236:237], v[88:89], v[148:149]
	v_pk_fma_f32 v[90:91], v[238:239], v[90:91], v[150:151]
	global_store_dwordx4 v248, v[92:95], s[42:43] offset:0
	global_store_dwordx4 v248, v[88:91], s[42:43] offset:16
	v_pk_mul_f32 v[144:145], v[92:93], v[240:241]
	v_pk_mul_f32 v[146:147], v[94:95], v[242:243]
	v_pk_mul_f32 v[148:149], v[88:89], v[244:245]
	v_pk_mul_f32 v[150:151], v[90:91], v[246:247]
	v_cvt_pk_bf16_f32 v144, v144, v145
	v_cvt_pk_bf16_f32 v145, v146, v147
	v_cvt_pk_bf16_f32 v146, v148, v149
	v_cvt_pk_bf16_f32 v147, v150, v151
	global_store_dwordx4 v249, v[144:147], s[2:3] offset:0
	v_mul_f32_e32 v148, v93, v93
	v_mul_f32_e32 v149, v95, v95
	v_mul_f32_e32 v150, v89, v89
	v_mul_f32_e32 v151, v91, v91
	v_fmac_f32_e32 v148, v92, v92
	v_fmac_f32_e32 v149, v94, v94
	v_fmac_f32_e32 v150, v88, v88
	v_fmac_f32_e32 v151, v90, v90
	v_add_f32_e32 v148, v148, v149
	v_add_f32_e32 v150, v150, v151
	v_add_f32_e32 v148, v148, v150
	v_add_f32_e32 v214, v214, v148
	v_pk_mul_f32 v[148:149], v[92:93], v[196:197]
	v_pk_mul_f32 v[150:151], v[94:95], v[198:199]
	v_pk_mul_f32 v[144:145], v[88:89], v[200:201]
	v_pk_mul_f32 v[146:147], v[90:91], v[202:203]
	v_mul_f32_e32 v149, v149, v149
	v_mul_f32_e32 v151, v151, v151
	v_fmac_f32_e32 v149, v148, v148
	v_fmac_f32_e32 v151, v150, v150
	v_add_f32_e32 v149, v149, v151
	v_mul_f32_e32 v145, v145, v145
	v_mul_f32_e32 v147, v147, v147
	v_fmac_f32_e32 v145, v144, v144
	v_fmac_f32_e32 v147, v146, v146
	v_add_f32_e32 v145, v145, v147
	v_add_f32_e32 v149, v149, v145
	v_add_f32_e32 v206, v206, v149
	s_add_u32 s42, s38, 0x30000
	s_addc_u32 s43, s39, 0
	s_add_u32 s2, s26, 0x18000
	s_addc_u32 s3, s27, 0
	s_waitcnt vmcnt(17)
	v_pk_fma_f32 v[76:77], v[232:233], v[76:77], v[152:153]
	v_pk_fma_f32 v[78:79], v[234:235], v[78:79], v[154:155]
	v_pk_fma_f32 v[72:73], v[236:237], v[72:73], v[156:157]
	v_pk_fma_f32 v[74:75], v[238:239], v[74:75], v[158:159]
	global_store_dwordx4 v248, v[76:79], s[42:43] offset:0
	global_store_dwordx4 v248, v[72:75], s[42:43] offset:16
	v_pk_mul_f32 v[152:153], v[76:77], v[240:241]
	v_pk_mul_f32 v[154:155], v[78:79], v[242:243]
	v_pk_mul_f32 v[156:157], v[72:73], v[244:245]
	v_pk_mul_f32 v[158:159], v[74:75], v[246:247]
	v_cvt_pk_bf16_f32 v152, v152, v153
	v_cvt_pk_bf16_f32 v153, v154, v155
	v_cvt_pk_bf16_f32 v154, v156, v157
	v_cvt_pk_bf16_f32 v155, v158, v159
	global_store_dwordx4 v249, v[152:155], s[2:3] offset:0
	v_mul_f32_e32 v156, v77, v77
	v_mul_f32_e32 v157, v79, v79
	v_mul_f32_e32 v158, v73, v73
	v_mul_f32_e32 v159, v75, v75
	v_fmac_f32_e32 v156, v76, v76
	v_fmac_f32_e32 v157, v78, v78
	v_fmac_f32_e32 v158, v72, v72
	v_fmac_f32_e32 v159, v74, v74
	v_add_f32_e32 v156, v156, v157
	v_add_f32_e32 v158, v158, v159
	v_add_f32_e32 v156, v156, v158
	v_add_f32_e32 v215, v215, v156
	v_pk_mul_f32 v[156:157], v[76:77], v[196:197]
	v_pk_mul_f32 v[158:159], v[78:79], v[198:199]
	v_pk_mul_f32 v[152:153], v[72:73], v[200:201]
	v_pk_mul_f32 v[154:155], v[74:75], v[202:203]
	v_mul_f32_e32 v157, v157, v157
	v_mul_f32_e32 v159, v159, v159
	v_fmac_f32_e32 v157, v156, v156
	v_fmac_f32_e32 v159, v158, v158
	v_add_f32_e32 v157, v157, v159
	v_mul_f32_e32 v153, v153, v153
	v_mul_f32_e32 v155, v155, v155
	v_fmac_f32_e32 v153, v152, v152
	v_fmac_f32_e32 v155, v154, v154
	v_add_f32_e32 v153, v153, v155
	v_add_f32_e32 v157, v157, v153
	v_add_f32_e32 v207, v207, v157
	s_add_u32 s42, s38, 0x80000
	s_addc_u32 s43, s39, 0
	s_add_u32 s2, s26, 0x40000
	s_addc_u32 s3, s27, 0
	s_waitcnt vmcnt(18)
; __device__ __forceinline__ unsigned cvt_pk_bf16(float lo, float hi) { unsigned r; asm volatile("v_cvt_pk_bf16_f32 %0, %1, %2" : "=v"(r) : "v"(lo), "v"(hi)); return r; }
; #define RES_LD(buf, pp) do { _Pragma("unroll") for (int j = 0; j < 2; ++j) { const int i_ = 2 * (pp) + j; const unsigned off_ = (row0 + (i_ >> 2) * HALF + (i_ & 3) * 16) * 1024u + col; \
;                 xq[buf][j][0] = *(const f32x4*)(xin + off_); xq[buf][j][1] = *(const f32x4*)(xin + off_ + 4); } } while (0)
;     static __device__ __forceinline__ void run(const f32x4 (&acc)[2][2][4][2], const Unit& u, int wr, int wc, int fr, int fq, const float* xin, float* xout, const float* gate, float gs, const float* lazy_ssq, const float* lazy_g, ...
;     ...
;                 if (DEEP) { if (pp < 3) RES_LD((pp + 1) & 1, pp + 1); } else RES_LD(pp & 1, pp);
; #pragma unroll
;                 for (int j = 0; j < 2; ++j) { const int i_ = 2 * pp + j, ai = i_ >> 2, m = i_ & 3; const unsigned off = (row0 + ai * HALF + m * 16) * 1024u + col;
;                     const f32x4 xi0 = xq[pp & 1][j][0], xi1 = xq[pp & 1][j][1];
;                     f32x4 xo0 = gv[0] * acc[ai][bj][m][0], xo1 = gv[1] * acc[ai][bj][m][1];
;                     if (LAZY) { xo0 = xo0 + xi0 * lg[0] * rl[ai][m]; xo1 = xo1 + xi1 * lg[1] * rl[ai][m]; } else { xo0 = xo0 + xi0; xo1 = xo1 + xi1; }
;                     *(f32x4*)(xout + off) = xo0; *(f32x4*)(xout + off + 4) = xo1;
;                     if (aout) { const f32x4 a0 = xo0 * wv[0], a1 = xo1 * wv[1]; u32x4 w; w.x = cvt_pk_bf16(a0[0], a0[1]); w.y = cvt_pk_bf16(a0[2], a0[3]); w.z = cvt_pk_bf16(a1[0], a1[1]); w.w = cvt_pk_bf16(a1[2], a1[3]);
;                         *(u32x4*)(aout + off) = w;
;                         sq[ai][m] += ((xo0[0] * xo0[0] + xo0[1] * xo0[1]) + (xo0[2] * xo0[2] + xo0[3] * xo0[3])) + ((xo1[0] * xo1[0] + xo1[1] * xo1[1]) + (xo1[2] * xo1[2] + xo1[3] * xo1[3]));
;                         if (WG2) { const f32x4 b0 = xo0 * w2[0], b1 = xo1 * w2[1]; sqb[ai][m] += ((b0[0] * b0[0] + b0[1] * b0[1]) + (b0[2] * b0[2] + b0[3] * b0[3])) + ((b1[0] * b1[0] + b1[1] * b1[1]) + (b1[2] * b1[2] + b1[3] * b1[3])); } } }
	v_pk_fma_f32 v[60:61], v[232:233], v[60:61], v[180:181]
	v_pk_fma_f32 v[62:63], v[234:235], v[62:63], v[182:183]
	v_pk_fma_f32 v[56:57], v[236:237], v[56:57], v[184:185]
	v_pk_fma_f32 v[58:59], v[238:239], v[58:59], v[186:187]
	global_store_dwordx4 v248, v[60:63], s[42:43] offset:0
	global_store_dwordx4 v248, v[56:59], s[42:43] offset:16
	v_pk_mul_f32 v[180:181], v[60:61], v[240:241]
	v_pk_mul_f32 v[182:183], v[62:63], v[242:243]
	v_pk_mul_f32 v[184:185], v[56:57], v[244:245]
	v_pk_mul_f32 v[186:187], v[58:59], v[246:247]
	v_cvt_pk_bf16_f32 v180, v180, v181
	v_cvt_pk_bf16_f32 v181, v182, v183
	v_cvt_pk_bf16_f32 v182, v184, v185
	v_cvt_pk_bf16_f32 v183, v186, v187
	global_store_dwordx4 v249, v[180:183], s[2:3] offset:0
	v_mul_f32_e32 v184, v61, v61
	v_mul_f32_e32 v185, v63, v63
	v_mul_f32_e32 v186, v57, v57
	v_mul_f32_e32 v187, v59, v59
	v_fmac_f32_e32 v184, v60, v60
	v_fmac_f32_e32 v185, v62, v62
	v_fmac_f32_e32 v186, v56, v56
	v_fmac_f32_e32 v187, v58, v58
	v_add_f32_e32 v184, v184, v185
	v_add_f32_e32 v186, v186, v187
	v_add_f32_e32 v184, v184, v186
	v_add_f32_e32 v172, v172, v184
	v_pk_mul_f32 v[184:185], v[60:61], v[196:197]
	v_pk_mul_f32 v[186:187], v[62:63], v[198:199]
	v_pk_mul_f32 v[180:181], v[56:57], v[200:201]
	v_pk_mul_f32 v[182:183], v[58:59], v[202:203]
	v_mul_f32_e32 v185, v185, v185
	v_mul_f32_e32 v187, v187, v187
	v_fmac_f32_e32 v185, v184, v184
	v_fmac_f32_e32 v187, v186, v186
	v_add_f32_e32 v185, v185, v187
	v_mul_f32_e32 v181, v181, v181
	v_mul_f32_e32 v183, v183, v183
	v_fmac_f32_e32 v181, v180, v180
	v_fmac_f32_e32 v183, v182, v182
	v_add_f32_e32 v181, v181, v183
	v_add_f32_e32 v185, v185, v181
	v_add_f32_e32 v208, v208, v185
	s_add_u32 s42, s38, 0x90000
	s_addc_u32 s43, s39, 0
	s_add_u32 s2, s26, 0x48000
	s_addc_u32 s3, s27, 0
	s_waitcnt vmcnt(19)
	v_pk_fma_f32 v[44:45], v[232:233], v[44:45], v[188:189]
	v_pk_fma_f32 v[46:47], v[234:235], v[46:47], v[190:191]
	v_pk_fma_f32 v[40:41], v[236:237], v[40:41], v[192:193]
	v_pk_fma_f32 v[42:43], v[238:239], v[42:43], v[194:195]
	global_store_dwordx4 v248, v[44:47], s[42:43] offset:0
	global_store_dwordx4 v248, v[40:43], s[42:43] offset:16
	v_pk_mul_f32 v[188:189], v[44:45], v[240:241]
	v_pk_mul_f32 v[190:191], v[46:47], v[242:243]
	v_pk_mul_f32 v[192:193], v[40:41], v[244:245]
	v_pk_mul_f32 v[194:195], v[42:43], v[246:247]
	v_cvt_pk_bf16_f32 v188, v188, v189
	v_cvt_pk_bf16_f32 v189, v190, v191
	v_cvt_pk_bf16_f32 v190, v192, v193
	v_cvt_pk_bf16_f32 v191, v194, v195
	global_store_dwordx4 v249, v[188:191], s[2:3] offset:0
	v_mul_f32_e32 v192, v45, v45
	v_mul_f32_e32 v193, v47, v47
	v_mul_f32_e32 v194, v41, v41
	v_mul_f32_e32 v195, v43, v43
	v_fmac_f32_e32 v192, v44, v44
	v_fmac_f32_e32 v193, v46, v46
	v_fmac_f32_e32 v194, v40, v40
	v_fmac_f32_e32 v195, v42, v42
	v_add_f32_e32 v192, v192, v193
	v_add_f32_e32 v194, v194, v195
	v_add_f32_e32 v192, v192, v194
	v_add_f32_e32 v173, v173, v192
	v_pk_mul_f32 v[192:193], v[44:45], v[196:197]
	v_pk_mul_f32 v[194:195], v[46:47], v[198:199]
	v_pk_mul_f32 v[188:189], v[40:41], v[200:201]
	v_pk_mul_f32 v[190:191], v[42:43], v[202:203]
	v_mul_f32_e32 v193, v193, v193
	v_mul_f32_e32 v195, v195, v195
	v_fmac_f32_e32 v193, v192, v192
	v_fmac_f32_e32 v195, v194, v194
	v_add_f32_e32 v193, v193, v195
	v_mul_f32_e32 v189, v189, v189
	v_mul_f32_e32 v191, v191, v191
	v_fmac_f32_e32 v189, v188, v188
	v_fmac_f32_e32 v191, v190, v190
	v_add_f32_e32 v189, v189, v191
	v_add_f32_e32 v193, v193, v189
	v_add_f32_e32 v209, v209, v193
	s_add_u32 s42, s38, 0xa0000
	s_addc_u32 s43, s39, 0
	s_add_u32 s2, s26, 0x50000
	s_addc_u32 s3, s27, 0
	s_waitcnt vmcnt(17)
	v_pk_fma_f32 v[28:29], v[232:233], v[28:29], v[128:129]
	v_pk_fma_f32 v[30:31], v[234:235], v[30:31], v[130:131]
	v_pk_fma_f32 v[24:25], v[236:237], v[24:25], v[132:133]
	v_pk_fma_f32 v[26:27], v[238:239], v[26:27], v[134:135]
	global_store_dwordx4 v248, v[28:31], s[42:43] offset:0
	global_store_dwordx4 v248, v[24:27], s[42:43] offset:16
	v_pk_mul_f32 v[128:129], v[28:29], v[240:241]
	v_pk_mul_f32 v[130:131], v[30:31], v[242:243]
	v_pk_mul_f32 v[132:133], v[24:25], v[244:245]
	v_pk_mul_f32 v[134:135], v[26:27], v[246:247]
	v_cvt_pk_bf16_f32 v128, v128, v129
	v_cvt_pk_bf16_f32 v129, v130, v131
	v_cvt_pk_bf16_f32 v130, v132, v133
	v_cvt_pk_bf16_f32 v131, v134, v135
	global_store_dwordx4 v249, v[128:131], s[2:3] offset:0
	v_mul_f32_e32 v132, v29, v29
	v_mul_f32_e32 v133, v31, v31
	v_mul_f32_e32 v134, v25, v25
	v_mul_f32_e32 v135, v27, v27
	v_fmac_f32_e32 v132, v28, v28
	v_fmac_f32_e32 v133, v30, v30
	v_fmac_f32_e32 v134, v24, v24
	v_fmac_f32_e32 v135, v26, v26
	v_add_f32_e32 v132, v132, v133
	v_add_f32_e32 v134, v134, v135
	v_add_f32_e32 v132, v132, v134
	v_add_f32_e32 v174, v174, v132
	v_pk_mul_f32 v[132:133], v[28:29], v[196:197]
	v_pk_mul_f32 v[134:135], v[30:31], v[198:199]
	v_pk_mul_f32 v[128:129], v[24:25], v[200:201]
	v_pk_mul_f32 v[130:131], v[26:27], v[202:203]
	v_mul_f32_e32 v133, v133, v133
	v_mul_f32_e32 v135, v135, v135
	v_fmac_f32_e32 v133, v132, v132
	v_fmac_f32_e32 v135, v134, v134
	v_add_f32_e32 v133, v133, v135
	v_mul_f32_e32 v129, v129, v129
	v_mul_f32_e32 v131, v131, v131
	v_fmac_f32_e32 v129, v128, v128
	v_fmac_f32_e32 v131, v130, v130
	v_add_f32_e32 v129, v129, v131
	v_add_f32_e32 v133, v133, v129
	v_add_f32_e32 v210, v210, v133
	s_add_u32 s42, s38, 0xb0000
	s_addc_u32 s43, s39, 0
	s_add_u32 s2, s26, 0x58000
	s_addc_u32 s3, s27, 0
	s_waitcnt vmcnt(15)
; __device__ __forceinline__ unsigned cvt_pk_bf16(float lo, float hi) { unsigned r; asm volatile("v_cvt_pk_bf16_f32 %0, %1, %2" : "=v"(r) : "v"(lo), "v"(hi)); return r; }
;     static __device__ __forceinline__ void run(const f32x4 (&acc)[2][2][4][2], const Unit& u, int wr, int wc, int fr, int fq, const float* xin, float* xout, const float* gate, float gs, const float* lazy_ssq, const float* lazy_g, ...
;     ...
;             f32x4 gv[2], lg[2], wv[2], w2[2];
; #pragma unroll
;             for (int n = 0; n < 2; ++n) {
;                 gv[n] = *(const f32x4*)(gate + (b * 9216u + col + 4 * n)) * gs;
;                 lg[n] = (f32x4){1.f, 1.f, 1.f, 1.f}; if (LAZY) lg[n] = *(const f32x4*)(lazy_g + col + 4 * n);
;                 wv[n] = (f32x4){0.f, 0.f, 0.f, 0.f}; w2[n] = (f32x4){1.f, 1.f, 1.f, 1.f};
;                 if (aout) { wv[n] = *(const f32x4*)(wg + col + 4 * n) * (*(const f32x4*)(wsc + (b * 9216u + col + 4 * n)) + 1.0f); if (WG2) { w2[n] = *(const f32x4*)(wg2 + col + 4 * n); wv[n] = wv[n] * w2[n]; } }
;             }
;             f32x4 xq[2][2][2];
;     ...
;             constexpr bool DEEP = !LAZY && !WG2;
;             if (DEEP) RES_LD(0, 0);
; #pragma unroll
;             for (int pp = 0; pp < 4; ++pp) {
;                 if (DEEP) { if (pp < 3) RES_LD((pp + 1) & 1, pp + 1); } else RES_LD(pp & 1, pp);
; #pragma unroll
;                 for (int j = 0; j < 2; ++j) { const int i_ = 2 * pp + j, ai = i_ >> 2, m = i_ & 3; const unsigned off = (row0 + ai * HALF + m * 16) * 1024u + col;
;                     const f32x4 xi0 = xq[pp & 1][j][0], xi1 = xq[pp & 1][j][1];
;                     f32x4 xo0 = gv[0] * acc[ai][bj][m][0], xo1 = gv[1] * acc[ai][bj][m][1];
;                     if (LAZY) { xo0 = xo0 + xi0 * lg[0] * rl[ai][m]; xo1 = xo1 + xi1 * lg[1] * rl[ai][m]; } else { xo0 = xo0 + xi0; xo1 = xo1 + xi1; }
;                     *(f32x4*)(xout + off) = xo0; *(f32x4*)(xout + off + 4) = xo1;
;                     if (aout) { const f32x4 a0 = xo0 * wv[0], a1 = xo1 * wv[1]; u32x4 w; w.x = cvt_pk_bf16(a0[0], a0[1]); w.y = cvt_pk_bf16(a0[2], a0[3]); w.z = cvt_pk_bf16(a1[0], a1[1]); w.w = cvt_pk_bf16(a1[2], a1[3]);
;                         *(u32x4*)(aout + off) = w;
;                         sq[ai][m] += ((xo0[0] * xo0[0] + xo0[1] * xo0[1]) + (xo0[2] * xo0[2] + xo0[3] * xo0[3])) + ((xo1[0] * xo1[0] + xo1[1] * xo1[1]) + (xo1[2] * xo1[2] + xo1[3] * xo1[3]));
	v_pk_fma_f32 v[12:13], v[232:233], v[12:13], v[136:137]
	v_pk_fma_f32 v[14:15], v[234:235], v[14:15], v[138:139]
	v_pk_fma_f32 v[8:9], v[236:237], v[8:9], v[140:141]
	v_pk_fma_f32 v[10:11], v[238:239], v[10:11], v[142:143]
	global_store_dwordx4 v248, v[12:15], s[42:43] offset:0
	global_store_dwordx4 v248, v[8:11], s[42:43] offset:16
	v_pk_mul_f32 v[136:137], v[12:13], v[240:241]
	v_pk_mul_f32 v[138:139], v[14:15], v[242:243]
	v_pk_mul_f32 v[140:141], v[8:9], v[244:245]
	v_pk_mul_f32 v[142:143], v[10:11], v[246:247]
	v_cvt_pk_bf16_f32 v136, v136, v137
	v_cvt_pk_bf16_f32 v137, v138, v139
	v_cvt_pk_bf16_f32 v138, v140, v141
	v_cvt_pk_bf16_f32 v139, v142, v143
	global_store_dwordx4 v249, v[136:139], s[2:3] offset:0
	v_mul_f32_e32 v140, v13, v13
	v_mul_f32_e32 v141, v15, v15
	v_mul_f32_e32 v142, v9, v9
	v_mul_f32_e32 v143, v11, v11
	v_fmac_f32_e32 v140, v12, v12
	v_fmac_f32_e32 v141, v14, v14
	v_fmac_f32_e32 v142, v8, v8
	v_fmac_f32_e32 v143, v10, v10
	v_add_f32_e32 v140, v140, v141
	v_add_f32_e32 v142, v142, v143
	v_add_f32_e32 v140, v140, v142
	v_add_f32_e32 v175, v175, v140
	v_pk_mul_f32 v[140:141], v[12:13], v[196:197]
	v_pk_mul_f32 v[142:143], v[14:15], v[198:199]
	v_pk_mul_f32 v[136:137], v[8:9], v[200:201]
	v_pk_mul_f32 v[138:139], v[10:11], v[202:203]
	v_mul_f32_e32 v141, v141, v141
	v_mul_f32_e32 v143, v143, v143
	v_fmac_f32_e32 v141, v140, v140
	v_fmac_f32_e32 v143, v142, v142
	v_add_f32_e32 v141, v141, v143
	v_mul_f32_e32 v137, v137, v137
	v_mul_f32_e32 v139, v139, v139
	v_fmac_f32_e32 v137, v136, v136
	v_fmac_f32_e32 v139, v138, v138
	v_add_f32_e32 v137, v137, v139
	v_add_f32_e32 v141, v141, v137
	v_add_f32_e32 v211, v211, v141
	global_load_dwordx4 v[232:235], v231, s[40:41] offset:512
	global_load_dwordx4 v[236:239], v231, s[40:41] offset:528
	global_load_dwordx4 v[240:243], v176, s[28:29] offset:512
	global_load_dwordx4 v[244:247], v176, s[28:29] offset:528
	global_load_dwordx4 v[188:191], v231, s[30:31] offset:512
	global_load_dwordx4 v[192:195], v231, s[30:31] offset:528
	global_load_dwordx4 v[196:199], v176, s[10:11] offset:512
	global_load_dwordx4 v[200:203], v176, s[10:11] offset:528
	s_mov_b64 s[8:9], s[34:35]
	global_load_dwordx4 v[128:131], v248, s[8:9] offset:512
	global_load_dwordx4 v[132:135], v248, s[8:9] offset:528
	s_add_u32 s8, s34, 0x10000
	s_addc_u32 s9, s35, 0
	global_load_dwordx4 v[136:139], v248, s[8:9] offset:512
	global_load_dwordx4 v[140:143], v248, s[8:9] offset:528
	s_add_u32 s8, s34, 0x20000
	s_addc_u32 s9, s35, 0
	global_load_dwordx4 v[144:147], v248, s[8:9] offset:512
	global_load_dwordx4 v[148:151], v248, s[8:9] offset:528
	s_add_u32 s8, s34, 0x30000
	s_addc_u32 s9, s35, 0
	global_load_dwordx4 v[152:155], v248, s[8:9] offset:512
	global_load_dwordx4 v[156:159], v248, s[8:9] offset:528
	s_add_u32 s8, s34, 0x80000
	s_addc_u32 s9, s35, 0
	global_load_dwordx4 v[180:183], v248, s[8:9] offset:512
	global_load_dwordx4 v[184:187], v248, s[8:9] offset:528
	s_waitcnt vmcnt(10)
	v_pk_mul_f32 v[232:233], s[36:37], v[232:233] op_sel_hi:[0,1]
	v_pk_mul_f32 v[234:235], s[36:37], v[234:235] op_sel_hi:[0,1]
	v_pk_mul_f32 v[236:237], s[36:37], v[236:237] op_sel_hi:[0,1]
	v_pk_mul_f32 v[238:239], s[36:37], v[238:239] op_sel_hi:[0,1]
	v_pk_add_f32 v[188:189], v[188:189], 1.0 op_sel_hi:[1,0]
	v_pk_add_f32 v[190:191], v[190:191], 1.0 op_sel_hi:[1,0]
	v_pk_add_f32 v[192:193], v[192:193], 1.0 op_sel_hi:[1,0]
	v_pk_add_f32 v[194:195], v[194:195], 1.0 op_sel_hi:[1,0]
	v_pk_mul_f32 v[240:241], v[240:241], v[188:189]
	v_pk_mul_f32 v[242:243], v[242:243], v[190:191]
	v_pk_mul_f32 v[244:245], v[244:245], v[192:193]
	v_pk_mul_f32 v[246:247], v[246:247], v[194:195]
	v_pk_mul_f32 v[240:241], v[240:241], v[196:197]
	v_pk_mul_f32 v[242:243], v[242:243], v[198:199]
	v_pk_mul_f32 v[244:245], v[244:245], v[200:201]
	v_pk_mul_f32 v[246:247], v[246:247], v[202:203]
	s_add_u32 s8, s34, 0x90000
	s_addc_u32 s9, s35, 0
	global_load_dwordx4 v[188:191], v248, s[8:9] offset:512
	global_load_dwordx4 v[192:195], v248, s[8:9] offset:528
	s_mov_b64 s[42:43], s[38:39]
	s_mov_b64 s[2:3], s[26:27]
	s_waitcnt vmcnt(10)
	v_pk_fma_f32 v[116:117], v[232:233], v[116:117], v[128:129]
	v_pk_fma_f32 v[118:119], v[234:235], v[118:119], v[130:131]
	v_pk_fma_f32 v[112:113], v[236:237], v[112:113], v[132:133]
	v_pk_fma_f32 v[114:115], v[238:239], v[114:115], v[134:135]
	global_store_dwordx4 v248, v[116:119], s[42:43] offset:512
	global_store_dwordx4 v248, v[112:115], s[42:43] offset:528
	v_pk_mul_f32 v[128:129], v[116:117], v[240:241]
	v_pk_mul_f32 v[130:131], v[118:119], v[242:243]
	v_pk_mul_f32 v[132:133], v[112:113], v[244:245]
	v_pk_mul_f32 v[134:135], v[114:115], v[246:247]
	v_cvt_pk_bf16_f32 v128, v128, v129
	v_cvt_pk_bf16_f32 v129, v130, v131
	v_cvt_pk_bf16_f32 v130, v132, v133
	v_cvt_pk_bf16_f32 v131, v134, v135
	global_store_dwordx4 v249, v[128:131], s[2:3] offset:256
	v_mul_f32_e32 v132, v117, v117
	v_mul_f32_e32 v133, v119, v119
	v_mul_f32_e32 v134, v113, v113
	v_mul_f32_e32 v135, v115, v115
	v_fmac_f32_e32 v132, v116, v116
	v_fmac_f32_e32 v133, v118, v118
	v_fmac_f32_e32 v134, v112, v112
	v_fmac_f32_e32 v135, v114, v114
	v_add_f32_e32 v132, v132, v133
	v_add_f32_e32 v134, v134, v135
	v_add_f32_e32 v132, v132, v134
	v_add_f32_e32 v212, v212, v132
	v_pk_mul_f32 v[132:133], v[116:117], v[196:197]
	v_pk_mul_f32 v[134:135], v[118:119], v[198:199]
	v_pk_mul_f32 v[128:129], v[112:113], v[200:201]
	v_pk_mul_f32 v[130:131], v[114:115], v[202:203]
	v_mul_f32_e32 v133, v133, v133
	v_mul_f32_e32 v135, v135, v135
	v_fmac_f32_e32 v133, v132, v132
	v_fmac_f32_e32 v135, v134, v134
	v_add_f32_e32 v133, v133, v135
	v_mul_f32_e32 v129, v129, v129
	v_mul_f32_e32 v131, v131, v131
	v_fmac_f32_e32 v129, v128, v128
	v_fmac_f32_e32 v131, v130, v130
	v_add_f32_e32 v129, v129, v131
	v_add_f32_e32 v133, v133, v129
	v_add_f32_e32 v204, v204, v133
	s_add_u32 s8, s34, 0xa0000
	s_addc_u32 s9, s35, 0
	global_load_dwordx4 v[128:131], v248, s[8:9] offset:512
	global_load_dwordx4 v[132:135], v248, s[8:9] offset:528
	s_add_u32 s42, s38, 0x10000
	s_addc_u32 s43, s39, 0
	s_add_u32 s2, s26, 0x8000
	s_addc_u32 s3, s27, 0
	s_waitcnt vmcnt(13)
; __device__ __forceinline__ unsigned cvt_pk_bf16(float lo, float hi) { unsigned r; asm volatile("v_cvt_pk_bf16_f32 %0, %1, %2" : "=v"(r) : "v"(lo), "v"(hi)); return r; }
; #define RES_LD(buf, pp) do { _Pragma("unroll") for (int j = 0; j < 2; ++j) { const int i_ = 2 * (pp) + j; const unsigned off_ = (row0 + (i_ >> 2) * HALF + (i_ & 3) * 16) * 1024u + col; \
;                 xq[buf][j][0] = *(const f32x4*)(xin + off_); xq[buf][j][1] = *(const f32x4*)(xin + off_ + 4); } } while (0)
;     static __device__ __forceinline__ void run(const f32x4 (&acc)[2][2][4][2], const Unit& u, int wr, int wc, int fr, int fq, const float* xin, float* xout, const float* gate, float gs, const float* lazy_ssq, const float* lazy_g, ...
;     ...
;                 if (DEEP) { if (pp < 3) RES_LD((pp + 1) & 1, pp + 1); } else RES_LD(pp & 1, pp);
; #pragma unroll
;                 for (int j = 0; j < 2; ++j) { const int i_ = 2 * pp + j, ai = i_ >> 2, m = i_ & 3; const unsigned off = (row0 + ai * HALF + m * 16) * 1024u + col;
;                     const f32x4 xi0 = xq[pp & 1][j][0], xi1 = xq[pp & 1][j][1];
;                     f32x4 xo0 = gv[0] * acc[ai][bj][m][0], xo1 = gv[1] * acc[ai][bj][m][1];
;                     if (LAZY) { xo0 = xo0 + xi0 * lg[0] * rl[ai][m]; xo1 = xo1 + xi1 * lg[1] * rl[ai][m]; } else { xo0 = xo0 + xi0; xo1 = xo1 + xi1; }
;                     *(f32x4*)(xout + off) = xo0; *(f32x4*)(xout + off + 4) = xo1;
;                     if (aout) { const f32x4 a0 = xo0 * wv[0], a1 = xo1 * wv[1]; u32x4 w; w.x = cvt_pk_bf16(a0[0], a0[1]); w.y = cvt_pk_bf16(a0[2], a0[3]); w.z = cvt_pk_bf16(a1[0], a1[1]); w.w = cvt_pk_bf16(a1[2], a1[3]);
;                         *(u32x4*)(aout + off) = w;
;                         sq[ai][m] += ((xo0[0] * xo0[0] + xo0[1] * xo0[1]) + (xo0[2] * xo0[2] + xo0[3] * xo0[3])) + ((xo1[0] * xo1[0] + xo1[1] * xo1[1]) + (xo1[2] * xo1[2] + xo1[3] * xo1[3]));
;                         if (WG2) { const f32x4 b0 = xo0 * w2[0], b1 = xo1 * w2[1]; sqb[ai][m] += ((b0[0] * b0[0] + b0[1] * b0[1]) + (b0[2] * b0[2] + b0[3] * b0[3])) + ((b1[0] * b1[0] + b1[1] * b1[1]) + (b1[2] * b1[2] + b1[3] * b1[3])); } } }
	v_pk_fma_f32 v[100:101], v[232:233], v[100:101], v[136:137]
	v_pk_fma_f32 v[102:103], v[234:235], v[102:103], v[138:139]
	v_pk_fma_f32 v[96:97], v[236:237], v[96:97], v[140:141]
	v_pk_fma_f32 v[98:99], v[238:239], v[98:99], v[142:143]
	global_store_dwordx4 v248, v[100:103], s[42:43] offset:512
	global_store_dwordx4 v248, v[96:99], s[42:43] offset:528
	v_pk_mul_f32 v[136:137], v[100:101], v[240:241]
	v_pk_mul_f32 v[138:139], v[102:103], v[242:243]
	v_pk_mul_f32 v[140:141], v[96:97], v[244:245]
	v_pk_mul_f32 v[142:143], v[98:99], v[246:247]
	v_cvt_pk_bf16_f32 v136, v136, v137
	v_cvt_pk_bf16_f32 v137, v138, v139
	v_cvt_pk_bf16_f32 v138, v140, v141
	v_cvt_pk_bf16_f32 v139, v142, v143
	global_store_dwordx4 v249, v[136:139], s[2:3] offset:256
	v_mul_f32_e32 v140, v101, v101
	v_mul_f32_e32 v141, v103, v103
	v_mul_f32_e32 v142, v97, v97
	v_mul_f32_e32 v143, v99, v99
	v_fmac_f32_e32 v140, v100, v100
	v_fmac_f32_e32 v141, v102, v102
	v_fmac_f32_e32 v142, v96, v96
	v_fmac_f32_e32 v143, v98, v98
	v_add_f32_e32 v140, v140, v141
	v_add_f32_e32 v142, v142, v143
	v_add_f32_e32 v140, v140, v142
	v_add_f32_e32 v213, v213, v140
	v_pk_mul_f32 v[140:141], v[100:101], v[196:197]
	v_pk_mul_f32 v[142:143], v[102:103], v[198:199]
	v_pk_mul_f32 v[136:137], v[96:97], v[200:201]
	v_pk_mul_f32 v[138:139], v[98:99], v[202:203]
	v_mul_f32_e32 v141, v141, v141
	v_mul_f32_e32 v143, v143, v143
	v_fmac_f32_e32 v141, v140, v140
	v_fmac_f32_e32 v143, v142, v142
	v_add_f32_e32 v141, v141, v143
	v_mul_f32_e32 v137, v137, v137
	v_mul_f32_e32 v139, v139, v139
	v_fmac_f32_e32 v137, v136, v136
	v_fmac_f32_e32 v139, v138, v138
	v_add_f32_e32 v137, v137, v139
	v_add_f32_e32 v141, v141, v137
	v_add_f32_e32 v205, v205, v141
	s_add_u32 s8, s34, 0xb0000
	s_addc_u32 s9, s35, 0
	global_load_dwordx4 v[136:139], v248, s[8:9] offset:512
	global_load_dwordx4 v[140:143], v248, s[8:9] offset:528
	s_add_u32 s42, s38, 0x20000
	s_addc_u32 s43, s39, 0
	s_add_u32 s2, s26, 0x10000
	s_addc_u32 s3, s27, 0
	s_waitcnt vmcnt(16)
	v_pk_fma_f32 v[84:85], v[232:233], v[84:85], v[144:145]
	v_pk_fma_f32 v[86:87], v[234:235], v[86:87], v[146:147]
	v_pk_fma_f32 v[80:81], v[236:237], v[80:81], v[148:149]
	v_pk_fma_f32 v[82:83], v[238:239], v[82:83], v[150:151]
	global_store_dwordx4 v248, v[84:87], s[42:43] offset:512
	global_store_dwordx4 v248, v[80:83], s[42:43] offset:528
	v_pk_mul_f32 v[144:145], v[84:85], v[240:241]
	v_pk_mul_f32 v[146:147], v[86:87], v[242:243]
	v_pk_mul_f32 v[148:149], v[80:81], v[244:245]
	v_pk_mul_f32 v[150:151], v[82:83], v[246:247]
	v_cvt_pk_bf16_f32 v144, v144, v145
	v_cvt_pk_bf16_f32 v145, v146, v147
	v_cvt_pk_bf16_f32 v146, v148, v149
	v_cvt_pk_bf16_f32 v147, v150, v151
	global_store_dwordx4 v249, v[144:147], s[2:3] offset:256
	v_mul_f32_e32 v148, v85, v85
	v_mul_f32_e32 v149, v87, v87
	v_mul_f32_e32 v150, v81, v81
	v_mul_f32_e32 v151, v83, v83
	v_fmac_f32_e32 v148, v84, v84
	v_fmac_f32_e32 v149, v86, v86
	v_fmac_f32_e32 v150, v80, v80
	v_fmac_f32_e32 v151, v82, v82
	v_add_f32_e32 v148, v148, v149
	v_add_f32_e32 v150, v150, v151
	v_add_f32_e32 v148, v148, v150
	v_add_f32_e32 v214, v214, v148
	v_pk_mul_f32 v[148:149], v[84:85], v[196:197]
	v_pk_mul_f32 v[150:151], v[86:87], v[198:199]
	v_pk_mul_f32 v[144:145], v[80:81], v[200:201]
	v_pk_mul_f32 v[146:147], v[82:83], v[202:203]
	v_mul_f32_e32 v149, v149, v149
	v_mul_f32_e32 v151, v151, v151
	v_fmac_f32_e32 v149, v148, v148
	v_fmac_f32_e32 v151, v150, v150
	v_add_f32_e32 v149, v149, v151
	v_mul_f32_e32 v145, v145, v145
	v_mul_f32_e32 v147, v147, v147
	v_fmac_f32_e32 v145, v144, v144
	v_fmac_f32_e32 v147, v146, v146
	v_add_f32_e32 v145, v145, v147
	v_add_f32_e32 v149, v149, v145
	v_add_f32_e32 v206, v206, v149
	s_add_u32 s42, s38, 0x30000
	s_addc_u32 s43, s39, 0
	s_add_u32 s2, s26, 0x18000
	s_addc_u32 s3, s27, 0
	s_waitcnt vmcnt(17)
	v_pk_fma_f32 v[68:69], v[232:233], v[68:69], v[152:153]
	v_pk_fma_f32 v[70:71], v[234:235], v[70:71], v[154:155]
	v_pk_fma_f32 v[64:65], v[236:237], v[64:65], v[156:157]
	v_pk_fma_f32 v[66:67], v[238:239], v[66:67], v[158:159]
	global_store_dwordx4 v248, v[68:71], s[42:43] offset:512
	global_store_dwordx4 v248, v[64:67], s[42:43] offset:528
	v_pk_mul_f32 v[152:153], v[68:69], v[240:241]
	v_pk_mul_f32 v[154:155], v[70:71], v[242:243]
	v_pk_mul_f32 v[156:157], v[64:65], v[244:245]
	v_pk_mul_f32 v[158:159], v[66:67], v[246:247]
	v_cvt_pk_bf16_f32 v152, v152, v153
	v_cvt_pk_bf16_f32 v153, v154, v155
	v_cvt_pk_bf16_f32 v154, v156, v157
	v_cvt_pk_bf16_f32 v155, v158, v159
	global_store_dwordx4 v249, v[152:155], s[2:3] offset:256
	v_mul_f32_e32 v156, v69, v69
	v_mul_f32_e32 v157, v71, v71
	v_mul_f32_e32 v158, v65, v65
	v_mul_f32_e32 v159, v67, v67
	v_fmac_f32_e32 v156, v68, v68
	v_fmac_f32_e32 v157, v70, v70
	v_fmac_f32_e32 v158, v64, v64
	v_fmac_f32_e32 v159, v66, v66
	v_add_f32_e32 v156, v156, v157
	v_add_f32_e32 v158, v158, v159
	v_add_f32_e32 v156, v156, v158
	v_add_f32_e32 v215, v215, v156
	v_pk_mul_f32 v[156:157], v[68:69], v[196:197]
	v_pk_mul_f32 v[158:159], v[70:71], v[198:199]
	v_pk_mul_f32 v[152:153], v[64:65], v[200:201]
	v_pk_mul_f32 v[154:155], v[66:67], v[202:203]
	v_mul_f32_e32 v157, v157, v157
	v_mul_f32_e32 v159, v159, v159
	v_fmac_f32_e32 v157, v156, v156
	v_fmac_f32_e32 v159, v158, v158
	v_add_f32_e32 v157, v157, v159
	v_mul_f32_e32 v153, v153, v153
	v_mul_f32_e32 v155, v155, v155
	v_fmac_f32_e32 v153, v152, v152
	v_fmac_f32_e32 v155, v154, v154
	v_add_f32_e32 v153, v153, v155
	v_add_f32_e32 v157, v157, v153
	v_add_f32_e32 v207, v207, v157
	s_add_u32 s42, s38, 0x80000
	s_addc_u32 s43, s39, 0
	s_add_u32 s2, s26, 0x40000
	s_addc_u32 s3, s27, 0
	s_waitcnt vmcnt(18)
; __device__ __forceinline__ unsigned cvt_pk_bf16(float lo, float hi) { unsigned r; asm volatile("v_cvt_pk_bf16_f32 %0, %1, %2" : "=v"(r) : "v"(lo), "v"(hi)); return r; }
; #define RES_LD(buf, pp) do { _Pragma("unroll") for (int j = 0; j < 2; ++j) { const int i_ = 2 * (pp) + j; const unsigned off_ = (row0 + (i_ >> 2) * HALF + (i_ & 3) * 16) * 1024u + col; \
;                 xq[buf][j][0] = *(const f32x4*)(xin + off_); xq[buf][j][1] = *(const f32x4*)(xin + off_ + 4); } } while (0)
;     static __device__ __forceinline__ void run(const f32x4 (&acc)[2][2][4][2], const Unit& u, int wr, int wc, int fr, int fq, const float* xin, float* xout, const float* gate, float gs, const float* lazy_ssq, const float* lazy_g, ...
;     ...
;                 if (DEEP) { if (pp < 3) RES_LD((pp + 1) & 1, pp + 1); } else RES_LD(pp & 1, pp);
; #pragma unroll
;                 for (int j = 0; j < 2; ++j) { const int i_ = 2 * pp + j, ai = i_ >> 2, m = i_ & 3; const unsigned off = (row0 + ai * HALF + m * 16) * 1024u + col;
;                     const f32x4 xi0 = xq[pp & 1][j][0], xi1 = xq[pp & 1][j][1];
;                     f32x4 xo0 = gv[0] * acc[ai][bj][m][0], xo1 = gv[1] * acc[ai][bj][m][1];
;                     if (LAZY) { xo0 = xo0 + xi0 * lg[0] * rl[ai][m]; xo1 = xo1 + xi1 * lg[1] * rl[ai][m]; } else { xo0 = xo0 + xi0; xo1 = xo1 + xi1; }
;                     *(f32x4*)(xout + off) = xo0; *(f32x4*)(xout + off + 4) = xo1;
;                     if (aout) { const f32x4 a0 = xo0 * wv[0], a1 = xo1 * wv[1]; u32x4 w; w.x = cvt_pk_bf16(a0[0], a0[1]); w.y = cvt_pk_bf16(a0[2], a0[3]); w.z = cvt_pk_bf16(a1[0], a1[1]); w.w = cvt_pk_bf16(a1[2], a1[3]);
;                         *(u32x4*)(aout + off) = w;
;                         sq[ai][m] += ((xo0[0] * xo0[0] + xo0[1] * xo0[1]) + (xo0[2] * xo0[2] + xo0[3] * xo0[3])) + ((xo1[0] * xo1[0] + xo1[1] * xo1[1]) + (xo1[2] * xo1[2] + xo1[3] * xo1[3]));
;                         if (WG2) { const f32x4 b0 = xo0 * w2[0], b1 = xo1 * w2[1]; sqb[ai][m] += ((b0[0] * b0[0] + b0[1] * b0[1]) + (b0[2] * b0[2] + b0[3] * b0[3])) + ((b1[0] * b1[0] + b1[1] * b1[1]) + (b1[2] * b1[2] + b1[3] * b1[3])); } } }
	v_pk_fma_f32 v[52:53], v[232:233], v[52:53], v[180:181]
	v_pk_fma_f32 v[54:55], v[234:235], v[54:55], v[182:183]
	v_pk_fma_f32 v[48:49], v[236:237], v[48:49], v[184:185]
	v_pk_fma_f32 v[50:51], v[238:239], v[50:51], v[186:187]
	global_store_dwordx4 v248, v[52:55], s[42:43] offset:512
	global_store_dwordx4 v248, v[48:51], s[42:43] offset:528
	v_pk_mul_f32 v[180:181], v[52:53], v[240:241]
	v_pk_mul_f32 v[182:183], v[54:55], v[242:243]
	v_pk_mul_f32 v[184:185], v[48:49], v[244:245]
	v_pk_mul_f32 v[186:187], v[50:51], v[246:247]
	v_cvt_pk_bf16_f32 v180, v180, v181
	v_cvt_pk_bf16_f32 v181, v182, v183
	v_cvt_pk_bf16_f32 v182, v184, v185
	v_cvt_pk_bf16_f32 v183, v186, v187
	global_store_dwordx4 v249, v[180:183], s[2:3] offset:256
	v_mul_f32_e32 v184, v53, v53
	v_mul_f32_e32 v185, v55, v55
	v_mul_f32_e32 v186, v49, v49
	v_mul_f32_e32 v187, v51, v51
	v_fmac_f32_e32 v184, v52, v52
	v_fmac_f32_e32 v185, v54, v54
	v_fmac_f32_e32 v186, v48, v48
	v_fmac_f32_e32 v187, v50, v50
	v_add_f32_e32 v184, v184, v185
	v_add_f32_e32 v186, v186, v187
	v_add_f32_e32 v184, v184, v186
	v_add_f32_e32 v172, v172, v184
	v_pk_mul_f32 v[184:185], v[52:53], v[196:197]
	v_pk_mul_f32 v[186:187], v[54:55], v[198:199]
	v_pk_mul_f32 v[180:181], v[48:49], v[200:201]
	v_pk_mul_f32 v[182:183], v[50:51], v[202:203]
	v_mul_f32_e32 v185, v185, v185
	v_mul_f32_e32 v187, v187, v187
	v_fmac_f32_e32 v185, v184, v184
	v_fmac_f32_e32 v187, v186, v186
	v_add_f32_e32 v185, v185, v187
	v_mul_f32_e32 v181, v181, v181
	v_mul_f32_e32 v183, v183, v183
	v_fmac_f32_e32 v181, v180, v180
	v_fmac_f32_e32 v183, v182, v182
	v_add_f32_e32 v181, v181, v183
	v_add_f32_e32 v185, v185, v181
	v_add_f32_e32 v208, v208, v185
	s_add_u32 s42, s38, 0x90000
	s_addc_u32 s43, s39, 0
	s_add_u32 s2, s26, 0x48000
	s_addc_u32 s3, s27, 0
	s_waitcnt vmcnt(19)
	v_pk_fma_f32 v[36:37], v[232:233], v[36:37], v[188:189]
	v_pk_fma_f32 v[38:39], v[234:235], v[38:39], v[190:191]
	v_pk_fma_f32 v[32:33], v[236:237], v[32:33], v[192:193]
	v_pk_fma_f32 v[34:35], v[238:239], v[34:35], v[194:195]
	global_store_dwordx4 v248, v[36:39], s[42:43] offset:512
	global_store_dwordx4 v248, v[32:35], s[42:43] offset:528
	v_pk_mul_f32 v[188:189], v[36:37], v[240:241]
	v_pk_mul_f32 v[190:191], v[38:39], v[242:243]
	v_pk_mul_f32 v[192:193], v[32:33], v[244:245]
	v_pk_mul_f32 v[194:195], v[34:35], v[246:247]
	v_cvt_pk_bf16_f32 v188, v188, v189
	v_cvt_pk_bf16_f32 v189, v190, v191
	v_cvt_pk_bf16_f32 v190, v192, v193
	v_cvt_pk_bf16_f32 v191, v194, v195
	global_store_dwordx4 v249, v[188:191], s[2:3] offset:256
	v_mul_f32_e32 v192, v37, v37
	v_mul_f32_e32 v193, v39, v39
	v_mul_f32_e32 v194, v33, v33
	v_mul_f32_e32 v195, v35, v35
	v_fmac_f32_e32 v192, v36, v36
	v_fmac_f32_e32 v193, v38, v38
	v_fmac_f32_e32 v194, v32, v32
	v_fmac_f32_e32 v195, v34, v34
	v_add_f32_e32 v192, v192, v193
	v_add_f32_e32 v194, v194, v195
	v_add_f32_e32 v192, v192, v194
	v_add_f32_e32 v173, v173, v192
	v_pk_mul_f32 v[192:193], v[36:37], v[196:197]
	v_pk_mul_f32 v[194:195], v[38:39], v[198:199]
	v_pk_mul_f32 v[188:189], v[32:33], v[200:201]
	v_pk_mul_f32 v[190:191], v[34:35], v[202:203]
	v_mul_f32_e32 v193, v193, v193
	v_mul_f32_e32 v195, v195, v195
	v_fmac_f32_e32 v193, v192, v192
	v_fmac_f32_e32 v195, v194, v194
	v_add_f32_e32 v193, v193, v195
	v_mul_f32_e32 v189, v189, v189
	v_mul_f32_e32 v191, v191, v191
	v_fmac_f32_e32 v189, v188, v188
	v_fmac_f32_e32 v191, v190, v190
	v_add_f32_e32 v189, v189, v191
	v_add_f32_e32 v193, v193, v189
	v_add_f32_e32 v209, v209, v193
	s_add_u32 s42, s38, 0xa0000
	s_addc_u32 s43, s39, 0
	s_add_u32 s2, s26, 0x50000
	s_addc_u32 s3, s27, 0
	s_waitcnt vmcnt(17)
	v_pk_fma_f32 v[20:21], v[232:233], v[20:21], v[128:129]
	v_pk_fma_f32 v[22:23], v[234:235], v[22:23], v[130:131]
	v_pk_fma_f32 v[16:17], v[236:237], v[16:17], v[132:133]
	v_pk_fma_f32 v[18:19], v[238:239], v[18:19], v[134:135]
	global_store_dwordx4 v248, v[20:23], s[42:43] offset:512
	global_store_dwordx4 v248, v[16:19], s[42:43] offset:528
	v_pk_mul_f32 v[128:129], v[20:21], v[240:241]
	v_pk_mul_f32 v[130:131], v[22:23], v[242:243]
	v_pk_mul_f32 v[132:133], v[16:17], v[244:245]
	v_pk_mul_f32 v[134:135], v[18:19], v[246:247]
	v_cvt_pk_bf16_f32 v128, v128, v129
	v_cvt_pk_bf16_f32 v129, v130, v131
	v_cvt_pk_bf16_f32 v130, v132, v133
	v_cvt_pk_bf16_f32 v131, v134, v135
	global_store_dwordx4 v249, v[128:131], s[2:3] offset:256
	v_mul_f32_e32 v132, v21, v21
	v_mul_f32_e32 v133, v23, v23
	v_mul_f32_e32 v134, v17, v17
	v_mul_f32_e32 v135, v19, v19
	v_fmac_f32_e32 v132, v20, v20
	v_fmac_f32_e32 v133, v22, v22
	v_fmac_f32_e32 v134, v16, v16
	v_fmac_f32_e32 v135, v18, v18
	v_add_f32_e32 v132, v132, v133
	v_add_f32_e32 v134, v134, v135
	v_add_f32_e32 v132, v132, v134
	v_add_f32_e32 v174, v174, v132
	v_pk_mul_f32 v[132:133], v[20:21], v[196:197]
	v_pk_mul_f32 v[134:135], v[22:23], v[198:199]
	v_pk_mul_f32 v[128:129], v[16:17], v[200:201]
	v_pk_mul_f32 v[130:131], v[18:19], v[202:203]
	v_mul_f32_e32 v133, v133, v133
	v_mul_f32_e32 v135, v135, v135
	v_fmac_f32_e32 v133, v132, v132
	v_fmac_f32_e32 v135, v134, v134
	v_add_f32_e32 v133, v133, v135
	v_mul_f32_e32 v129, v129, v129
	v_mul_f32_e32 v131, v131, v131
	v_fmac_f32_e32 v129, v128, v128
	v_fmac_f32_e32 v131, v130, v130
	v_add_f32_e32 v129, v129, v131
	v_add_f32_e32 v133, v133, v129
	v_add_f32_e32 v210, v210, v133
	s_add_u32 s42, s38, 0xb0000
	s_addc_u32 s43, s39, 0
	s_add_u32 s2, s26, 0x58000
	s_addc_u32 s3, s27, 0
	s_waitcnt vmcnt(15)
; __device__ __forceinline__ unsigned cvt_pk_bf16(float lo, float hi) { unsigned r; asm volatile("v_cvt_pk_bf16_f32 %0, %1, %2" : "=v"(r) : "v"(lo), "v"(hi)); return r; }
;     static __device__ __forceinline__ void run(const f32x4 (&acc)[2][2][4][2], const Unit& u, int wr, int wc, int fr, int fq, const float* xin, float* xout, const float* gate, float gs, const float* lazy_ssq, const float* lazy_g, ...
;     ...
;                 for (int j = 0; j < 2; ++j) { const int i_ = 2 * pp + j, ai = i_ >> 2, m = i_ & 3; const unsigned off = (row0 + ai * HALF + m * 16) * 1024u + col;
;                     const f32x4 xi0 = xq[pp & 1][j][0], xi1 = xq[pp & 1][j][1];
;                     f32x4 xo0 = gv[0] * acc[ai][bj][m][0], xo1 = gv[1] * acc[ai][bj][m][1];
;                     if (LAZY) { xo0 = xo0 + xi0 * lg[0] * rl[ai][m]; xo1 = xo1 + xi1 * lg[1] * rl[ai][m]; } else { xo0 = xo0 + xi0; xo1 = xo1 + xi1; }
;                     *(f32x4*)(xout + off) = xo0; *(f32x4*)(xout + off + 4) = xo1;
;                     if (aout) { const f32x4 a0 = xo0 * wv[0], a1 = xo1 * wv[1]; u32x4 w; w.x = cvt_pk_bf16(a0[0], a0[1]); w.y = cvt_pk_bf16(a0[2], a0[3]); w.z = cvt_pk_bf16(a1[0], a1[1]); w.w = cvt_pk_bf16(a1[2], a1[3]);
;                         *(u32x4*)(aout + off) = w;
;                         sq[ai][m] += ((xo0[0] * xo0[0] + xo0[1] * xo0[1]) + (xo0[2] * xo0[2] + xo0[3] * xo0[3])) + ((xo1[0] * xo1[0] + xo1[1] * xo1[1]) + (xo1[2] * xo1[2] + xo1[3] * xo1[3]));
;                         if (WG2) { const f32x4 b0 = xo0 * w2[0], b1 = xo1 * w2[1]; sqb[ai][m] += ((b0[0] * b0[0] + b0[1] * b0[1]) + (b0[2] * b0[2] + b0[3] * b0[3])) + ((b1[0] * b1[0] + b1[1] * b1[1]) + (b1[2] * b1[2] + b1[3] * b1[3])); } } }
;     ...
;         if (aout) {
; #pragma unroll
;             for (int ai = 0; ai < 2; ++ai)
; #pragma unroll
;                 for (int m = 0; m < 4; ++m) { float s = sq[ai][m]; s = xadd<16>(s); s = xadd<32>(s);
;                     float sb = sqb[ai][m]; if (WG2) { sb = xadd<16>(sb); sb = xadd<32>(sb); }
;                     if (fq == 0) { unsafeAtomicAdd(ssq_out + (row0 + ai * HALF + m * 16), s); if (WG2) unsafeAtomicAdd(ssqB_out + (row0 + ai * HALF + m * 16), sb); } }
	v_pk_fma_f32 v[4:5], v[232:233], v[4:5], v[136:137]
	v_pk_fma_f32 v[6:7], v[234:235], v[6:7], v[138:139]
	v_pk_fma_f32 v[0:1], v[236:237], v[0:1], v[140:141]
	v_pk_fma_f32 v[2:3], v[238:239], v[2:3], v[142:143]
	global_store_dwordx4 v248, v[4:7], s[42:43] offset:512
	global_store_dwordx4 v248, v[0:3], s[42:43] offset:528
	v_pk_mul_f32 v[136:137], v[4:5], v[240:241]
	v_pk_mul_f32 v[138:139], v[6:7], v[242:243]
	v_pk_mul_f32 v[140:141], v[0:1], v[244:245]
	v_pk_mul_f32 v[142:143], v[2:3], v[246:247]
	v_cvt_pk_bf16_f32 v136, v136, v137
	v_cvt_pk_bf16_f32 v137, v138, v139
	v_cvt_pk_bf16_f32 v138, v140, v141
	v_cvt_pk_bf16_f32 v139, v142, v143
	global_store_dwordx4 v249, v[136:139], s[2:3] offset:256
	v_mul_f32_e32 v140, v5, v5
	v_mul_f32_e32 v141, v7, v7
	v_mul_f32_e32 v142, v1, v1
	v_mul_f32_e32 v143, v3, v3
	v_fmac_f32_e32 v140, v4, v4
	v_fmac_f32_e32 v141, v6, v6
	v_fmac_f32_e32 v142, v0, v0
	v_fmac_f32_e32 v143, v2, v2
	v_add_f32_e32 v140, v140, v141
	v_add_f32_e32 v142, v142, v143
	v_add_f32_e32 v140, v140, v142
	v_add_f32_e32 v175, v175, v140
	v_pk_mul_f32 v[140:141], v[4:5], v[196:197]
	v_pk_mul_f32 v[142:143], v[6:7], v[198:199]
	v_pk_mul_f32 v[136:137], v[0:1], v[200:201]
	v_pk_mul_f32 v[138:139], v[2:3], v[202:203]
	v_mul_f32_e32 v141, v141, v141
	v_mul_f32_e32 v143, v143, v143
	v_fmac_f32_e32 v141, v140, v140
	v_fmac_f32_e32 v143, v142, v142
	v_add_f32_e32 v141, v141, v143
	v_mul_f32_e32 v137, v137, v137
	v_mul_f32_e32 v139, v139, v139
	v_fmac_f32_e32 v137, v136, v136
	v_fmac_f32_e32 v139, v138, v138
	v_add_f32_e32 v137, v137, v139
	v_add_f32_e32 v141, v141, v137
	v_add_f32_e32 v211, v211, v141
	ds_swizzle_b32 v128, v212 offset:swizzle(SWAP,16)
	ds_swizzle_b32 v129, v213 offset:swizzle(SWAP,16)
	ds_swizzle_b32 v130, v214 offset:swizzle(SWAP,16)
	ds_swizzle_b32 v131, v215 offset:swizzle(SWAP,16)
	ds_swizzle_b32 v132, v172 offset:swizzle(SWAP,16)
	ds_swizzle_b32 v133, v173 offset:swizzle(SWAP,16)
	ds_swizzle_b32 v134, v174 offset:swizzle(SWAP,16)
	ds_swizzle_b32 v135, v175 offset:swizzle(SWAP,16)
	ds_swizzle_b32 v136, v204 offset:swizzle(SWAP,16)
	ds_swizzle_b32 v137, v205 offset:swizzle(SWAP,16)
	ds_swizzle_b32 v138, v206 offset:swizzle(SWAP,16)
	ds_swizzle_b32 v139, v207 offset:swizzle(SWAP,16)
	ds_swizzle_b32 v140, v208 offset:swizzle(SWAP,16)
	ds_swizzle_b32 v141, v209 offset:swizzle(SWAP,16)
	ds_swizzle_b32 v142, v210 offset:swizzle(SWAP,16)
	ds_swizzle_b32 v143, v211 offset:swizzle(SWAP,16)
	s_waitcnt lgkmcnt(0)
	v_add_f32_e32 v212, v212, v128
	v_add_f32_e32 v213, v213, v129
	v_add_f32_e32 v214, v214, v130
	v_add_f32_e32 v215, v215, v131
	v_add_f32_e32 v172, v172, v132
	v_add_f32_e32 v173, v173, v133
	v_add_f32_e32 v174, v174, v134
	v_add_f32_e32 v175, v175, v135
	v_add_f32_e32 v204, v204, v136
	v_add_f32_e32 v205, v205, v137
	v_add_f32_e32 v206, v206, v138
	v_add_f32_e32 v207, v207, v139
	v_add_f32_e32 v208, v208, v140
	v_add_f32_e32 v209, v209, v141
	v_add_f32_e32 v210, v210, v142
	v_add_f32_e32 v211, v211, v143
	v_mov_b32_e32 v128, v212
	v_mov_b32_e32 v129, v213
	v_mov_b32_e32 v130, v214
	v_mov_b32_e32 v131, v215
	v_mov_b32_e32 v132, v172
	v_mov_b32_e32 v133, v173
	v_mov_b32_e32 v134, v174
	v_mov_b32_e32 v135, v175
	v_mov_b32_e32 v136, v204
	v_mov_b32_e32 v137, v205
	v_mov_b32_e32 v138, v206
	v_mov_b32_e32 v139, v207
	v_mov_b32_e32 v140, v208
	v_mov_b32_e32 v141, v209
	v_mov_b32_e32 v142, v210
	v_mov_b32_e32 v143, v211
	s_nop 1
	v_permlane32_swap_b32_e32 v212, v128
	v_permlane32_swap_b32_e32 v213, v129
	v_permlane32_swap_b32_e32 v214, v130
	v_permlane32_swap_b32_e32 v215, v131
	v_permlane32_swap_b32_e32 v172, v132
	v_permlane32_swap_b32_e32 v173, v133
	v_permlane32_swap_b32_e32 v174, v134
	v_permlane32_swap_b32_e32 v175, v135
	v_permlane32_swap_b32_e32 v204, v136
	v_permlane32_swap_b32_e32 v205, v137
	v_permlane32_swap_b32_e32 v206, v138
	v_permlane32_swap_b32_e32 v207, v139
	v_permlane32_swap_b32_e32 v208, v140
	v_permlane32_swap_b32_e32 v209, v141
	v_permlane32_swap_b32_e32 v210, v142
	v_permlane32_swap_b32_e32 v211, v143
	v_mov_b32_e32 v144, 0x20880
	ds_read_b128 v[144:147], v144
	s_lshl_b32 s8, s63, 8
	s_lshl_b32 s9, s65, 6
	s_add_i32 s8, s8, s9
	v_or_b32_e32 v176, s8, v230
	v_lshlrev_b32_e32 v176, 2, v176
	s_waitcnt lgkmcnt(0)
	v_readfirstlane_b32 s10, v144
	v_readfirstlane_b32 s11, v145
	v_readfirstlane_b32 s28, v146
	v_readfirstlane_b32 s29, v147
	s_mov_b64 s[8:9], exec
	s_mov_b64 exec, 0xffff
	v_add_f32_e32 v212, v212, v128
	v_add_f32_e32 v213, v213, v129
	v_add_f32_e32 v214, v214, v130
	v_add_f32_e32 v215, v215, v131
	v_add_f32_e32 v172, v172, v132
	v_add_f32_e32 v173, v173, v133
	v_add_f32_e32 v174, v174, v134
	v_add_f32_e32 v175, v175, v135
	v_add_f32_e32 v204, v204, v136
	v_add_f32_e32 v205, v205, v137
	v_add_f32_e32 v206, v206, v138
	v_add_f32_e32 v207, v207, v139
	v_add_f32_e32 v208, v208, v140
	v_add_f32_e32 v209, v209, v141
	v_add_f32_e32 v210, v210, v142
	v_add_f32_e32 v211, v211, v143
	s_nop 3
	global_atomic_add_f32 v176, v212, s[10:11]
	global_atomic_add_f32 v176, v213, s[10:11] offset:64
	global_atomic_add_f32 v176, v214, s[10:11] offset:128
	global_atomic_add_f32 v176, v215, s[10:11] offset:192
	global_atomic_add_f32 v176, v172, s[10:11] offset:512
	global_atomic_add_f32 v176, v173, s[10:11] offset:576
	global_atomic_add_f32 v176, v174, s[10:11] offset:640
	global_atomic_add_f32 v176, v175, s[10:11] offset:704
	global_atomic_add_f32 v176, v204, s[28:29]
	global_atomic_add_f32 v176, v205, s[28:29] offset:64
	global_atomic_add_f32 v176, v206, s[28:29] offset:128
	global_atomic_add_f32 v176, v207, s[28:29] offset:192
	global_atomic_add_f32 v176, v208, s[28:29] offset:512
	global_atomic_add_f32 v176, v209, s[28:29] offset:576
	global_atomic_add_f32 v176, v210, s[28:29] offset:640
	global_atomic_add_f32 v176, v211, s[28:29] offset:704
	s_mov_b64 exec, s[8:9]
	s_mov_b64 s[2:3], 0
	s_mov_b64 s[26:27], 0
